# B (windowed) attention tile loop rewritten (fixed 5-tile window program per wave, 2-stage pipeline, prefetched fragments); write-through (sc0 sc1) stores for the coalesced 16-byte W_in z-tile and W_ou
# speedup vs baseline: 1.0727x; 1.0204x over previous
.LBB0_92:
	v_add_u32_e32 v0, s19, v131
	v_ashrrev_i32_e32 v109, 5, v0
	v_add_u32_e32 v68, 0x200, v0
	v_add_u32_e32 v100, s90, v109
	v_ashrrev_i32_e32 v103, 5, v68
	v_ashrrev_i32_e32 v101, 31, v100
	v_add_u32_e32 v96, s90, v103
	v_lshlrev_b64 v[104:105], 12, v[100:101]
	v_ashrrev_i32_e32 v97, 31, v96
	s_waitcnt lgkmcnt(0)
	v_lshl_add_u64 v[66:67], v[82:83], 0, v[104:105]
	v_lshlrev_b64 v[98:99], 12, v[96:97]
	v_lshl_add_u64 v[68:69], v[82:83], 0, v[98:99]
	global_load_dwordx4 v[78:81], v[66:67], off nt
	global_load_dwordx4 v[74:77], v[68:69], off nt
	v_add_u32_e32 v66, 0x400, v0
	v_add_u32_e32 v0, 0x600, v0
	v_ashrrev_i32_e32 v102, 5, v66
	v_ashrrev_i32_e32 v0, 5, v0
	v_add_u32_e32 v92, s90, v102
	v_add_u32_e32 v88, s90, v0
	v_ashrrev_i32_e32 v93, 31, v92
	v_ashrrev_i32_e32 v89, 31, v88
	v_lshlrev_b64 v[94:95], 12, v[92:93]
	v_lshlrev_b64 v[90:91], 12, v[88:89]
	v_lshl_add_u64 v[66:67], v[82:83], 0, v[94:95]
	v_lshl_add_u64 v[68:69], v[82:83], 0, v[90:91]
	global_load_dwordx4 v[70:73], v[66:67], off nt
	s_nop 0
	global_load_dwordx4 v[66:69], v[68:69], off nt
	v_lshlrev_b32_e32 v110, 9, v109
	v_xor_b32_e32 v109, v109, v131
	v_lshlrev_b32_e32 v109, 4, v109
	v_and_b32_e32 v109, 0x1f0, v109
	v_add3_u32 v109, 0, v110, v109
	ds_read_b128 v[110:113], v109
	v_cndmask_b32_e64 v109, 0, 1, s[40:41]
	v_cmp_ne_u32_e64 s[38:39], 1, v109
	v_lshl_add_u64 v[104:105], v[84:85], 0, v[104:105]
	s_andn2_b64 vcc, exec, s[40:41]
	s_waitcnt vmcnt(3) lgkmcnt(0)
	v_pk_add_f32 v[78:79], v[78:79], v[110:111]
	v_pk_add_f32 v[80:81], v[80:81], v[112:113]
	global_store_dwordx4 v[104:105], v[78:81], off sc0 sc1
	s_cbranch_vccnz .LBB0_96
	v_cvt_pk_bf16_f32 v104, v78, v79
	v_pk_mul_f32 v[78:79], v[78:79], v[78:79]
	v_cvt_pk_bf16_f32 v105, v80, v81
	v_pk_mul_f32 v[80:81], v[80:81], v[80:81]
	v_add_f32_e32 v78, v78, v79
	v_cmp_lt_i32_e32 vcc, v228, v222
	v_add_f32_e32 v78, v78, v80
	v_add_f32_e32 v78, v78, v81
	v_cndmask_b32_e32 v79, v221, v228, vcc
	v_lshlrev_b32_e32 v79, 2, v79
	ds_bpermute_b32 v79, v79, v78
	v_cmp_lt_i32_e32 vcc, v227, v222
	v_mad_i64_i32 v[110:111], s[8:9], v100, s33, v[86:87]
	global_store_dwordx2 v[110:111], v[104:105], off sc0 sc1
	s_waitcnt lgkmcnt(0)
	v_add_f32_e32 v78, v78, v79
	v_cndmask_b32_e32 v79, v221, v227, vcc
	v_lshlrev_b32_e32 v79, 2, v79
	ds_bpermute_b32 v79, v79, v78
	v_cmp_lt_i32_e32 vcc, v226, v222
	s_waitcnt lgkmcnt(0)
	v_add_f32_e32 v78, v78, v79
	v_cndmask_b32_e32 v79, v221, v226, vcc
	v_lshlrev_b32_e32 v79, 2, v79
	ds_bpermute_b32 v79, v79, v78
	v_cmp_lt_i32_e32 vcc, v225, v222
	s_waitcnt lgkmcnt(0)
	v_add_f32_e32 v78, v78, v79
	v_cndmask_b32_e32 v79, v221, v225, vcc
	v_lshlrev_b32_e32 v79, 2, v79
	ds_bpermute_b32 v79, v79, v78
	v_cmp_lt_i32_e32 vcc, v217, v222
	s_waitcnt lgkmcnt(0)
	v_add_f32_e32 v78, v78, v79
	v_cndmask_b32_e32 v79, v221, v217, vcc
	v_lshlrev_b32_e32 v79, 2, v79
	ds_bpermute_b32 v79, v79, v78
	s_and_saveexec_b64 s[8:9], s[36:37]
	s_cbranch_execz .LBB0_95
	s_waitcnt lgkmcnt(0)
	v_add_f32_e32 v80, v78, v79
	v_lshlrev_b64 v[78:79], 5, v[100:101]
	v_lshl_add_u64 v[78:79], s[0:1], 0, v[78:79]
	global_store_dword v[78:79], v80, off sc0 sc1

.LBB0_96:
	s_waitcnt lgkmcnt(0)
	v_xor_b32_e32 v79, v103, v131
	v_lshlrev_b32_e32 v79, 4, v79
	v_lshlrev_b32_e32 v78, 9, v103
	v_and_b32_e32 v79, 0x1f0, v79
	v_add3_u32 v78, 0, v78, v79
	ds_read_b128 v[78:81], v78
	v_lshl_add_u64 v[98:99], v[84:85], 0, v[98:99]
	s_and_b64 vcc, exec, s[38:39]
	s_waitcnt vmcnt(3) lgkmcnt(0)
	v_pk_add_f32 v[74:75], v[74:75], v[78:79]
	v_pk_add_f32 v[76:77], v[76:77], v[80:81]
	global_store_dwordx4 v[98:99], v[74:77], off sc0 sc1
	s_cbranch_vccnz .LBB0_100
	v_cvt_pk_bf16_f32 v78, v74, v75
	v_pk_mul_f32 v[74:75], v[74:75], v[74:75]
	v_cvt_pk_bf16_f32 v79, v76, v77
	v_pk_mul_f32 v[76:77], v[76:77], v[76:77]
	v_add_f32_e32 v74, v74, v75
	v_cmp_lt_i32_e32 vcc, v228, v222
	v_add_f32_e32 v74, v74, v76
	v_add_f32_e32 v74, v74, v77
	v_cndmask_b32_e32 v75, v221, v228, vcc
	v_lshlrev_b32_e32 v75, 2, v75
	ds_bpermute_b32 v75, v75, v74
	v_cmp_lt_i32_e32 vcc, v227, v222
	v_mad_i64_i32 v[80:81], s[8:9], v96, s33, v[86:87]
	global_store_dwordx2 v[80:81], v[78:79], off sc0 sc1
	s_waitcnt lgkmcnt(0)
	v_add_f32_e32 v74, v74, v75
	v_cndmask_b32_e32 v75, v221, v227, vcc
	v_lshlrev_b32_e32 v75, 2, v75
	ds_bpermute_b32 v75, v75, v74
	v_cmp_lt_i32_e32 vcc, v226, v222
	s_waitcnt lgkmcnt(0)
	v_add_f32_e32 v74, v74, v75
	v_cndmask_b32_e32 v75, v221, v226, vcc
	v_lshlrev_b32_e32 v75, 2, v75
	ds_bpermute_b32 v75, v75, v74
	v_cmp_lt_i32_e32 vcc, v225, v222
	s_waitcnt lgkmcnt(0)
	v_add_f32_e32 v74, v74, v75
	v_cndmask_b32_e32 v75, v221, v225, vcc
	v_lshlrev_b32_e32 v75, 2, v75
	ds_bpermute_b32 v75, v75, v74
	v_cmp_lt_i32_e32 vcc, v217, v222
	s_waitcnt lgkmcnt(0)
	v_add_f32_e32 v74, v74, v75
	v_cndmask_b32_e32 v75, v221, v217, vcc
	v_lshlrev_b32_e32 v75, 2, v75
	ds_bpermute_b32 v75, v75, v74
	s_and_saveexec_b64 s[8:9], s[36:37]
	s_cbranch_execz .LBB0_99
	s_waitcnt lgkmcnt(0)
	v_add_f32_e32 v76, v74, v75
	v_lshlrev_b64 v[74:75], 5, v[96:97]
	v_lshl_add_u64 v[74:75], s[0:1], 0, v[74:75]
	global_store_dword v[74:75], v76, off sc0 sc1

.LBB0_100:
	s_waitcnt lgkmcnt(0)
	v_xor_b32_e32 v75, v102, v131
	v_lshlrev_b32_e32 v75, 4, v75
	v_lshlrev_b32_e32 v74, 9, v102
	v_and_b32_e32 v75, 0x1f0, v75
	v_add3_u32 v74, 0, v74, v75
	ds_read_b128 v[74:77], v74
	v_lshl_add_u64 v[78:79], v[84:85], 0, v[94:95]
	s_and_b64 vcc, exec, s[38:39]
	s_waitcnt vmcnt(3) lgkmcnt(0)
	v_pk_add_f32 v[70:71], v[70:71], v[74:75]
	v_pk_add_f32 v[72:73], v[72:73], v[76:77]
	global_store_dwordx4 v[78:79], v[70:73], off sc0 sc1
	s_cbranch_vccnz .LBB0_104
	v_cvt_pk_bf16_f32 v74, v70, v71
	v_pk_mul_f32 v[70:71], v[70:71], v[70:71]
	v_cvt_pk_bf16_f32 v75, v72, v73
	v_pk_mul_f32 v[72:73], v[72:73], v[72:73]
	v_add_f32_e32 v70, v70, v71
	v_cmp_lt_i32_e32 vcc, v228, v222
	v_add_f32_e32 v70, v70, v72
	v_add_f32_e32 v70, v70, v73
	v_cndmask_b32_e32 v71, v221, v228, vcc
	v_lshlrev_b32_e32 v71, 2, v71
	ds_bpermute_b32 v71, v71, v70
	v_cmp_lt_i32_e32 vcc, v227, v222
	v_mad_i64_i32 v[76:77], s[8:9], v92, s33, v[86:87]
	global_store_dwordx2 v[76:77], v[74:75], off sc0 sc1
	s_waitcnt lgkmcnt(0)
	v_add_f32_e32 v70, v70, v71
	v_cndmask_b32_e32 v71, v221, v227, vcc
	v_lshlrev_b32_e32 v71, 2, v71
	ds_bpermute_b32 v71, v71, v70
	v_cmp_lt_i32_e32 vcc, v226, v222
	s_waitcnt lgkmcnt(0)
	v_add_f32_e32 v70, v70, v71
	v_cndmask_b32_e32 v71, v221, v226, vcc
	v_lshlrev_b32_e32 v71, 2, v71
	ds_bpermute_b32 v71, v71, v70
	v_cmp_lt_i32_e32 vcc, v225, v222
	s_waitcnt lgkmcnt(0)
	v_add_f32_e32 v70, v70, v71
	v_cndmask_b32_e32 v71, v221, v225, vcc
	v_lshlrev_b32_e32 v71, 2, v71
	ds_bpermute_b32 v71, v71, v70
	v_cmp_lt_i32_e32 vcc, v217, v222
	s_waitcnt lgkmcnt(0)
	v_add_f32_e32 v70, v70, v71
	v_cndmask_b32_e32 v71, v221, v217, vcc
	v_lshlrev_b32_e32 v71, 2, v71
	ds_bpermute_b32 v71, v71, v70
	s_and_saveexec_b64 s[8:9], s[36:37]
	s_cbranch_execz .LBB0_103
	s_waitcnt lgkmcnt(0)
	v_add_f32_e32 v72, v70, v71
	v_lshlrev_b64 v[70:71], 5, v[92:93]
	v_lshl_add_u64 v[70:71], s[0:1], 0, v[70:71]
	global_store_dword v[70:71], v72, off sc0 sc1

.LBB0_104:
	s_nop 0
	v_lshlrev_b32_e32 v70, 9, v0
	v_xor_b32_e32 v0, v0, v131
	v_lshlrev_b32_e32 v0, 4, v0
	v_and_b32_e32 v0, 0x1f0, v0
	v_add3_u32 v0, 0, v70, v0
	s_waitcnt lgkmcnt(0)
	ds_read_b128 v[70:73], v0
	v_lshl_add_u64 v[74:75], v[84:85], 0, v[90:91]
	s_and_b64 vcc, exec, s[38:39]
	s_waitcnt vmcnt(3) lgkmcnt(0)
	v_pk_add_f32 v[66:67], v[66:67], v[70:71]
	v_pk_add_f32 v[68:69], v[68:69], v[72:73]
	global_store_dwordx4 v[74:75], v[66:69], off sc0 sc1
	s_cbranch_vccnz .LBB0_91
	v_cvt_pk_bf16_f32 v70, v66, v67
	v_pk_mul_f32 v[66:67], v[66:67], v[66:67]
	v_cvt_pk_bf16_f32 v71, v68, v69
	v_pk_mul_f32 v[68:69], v[68:69], v[68:69]
	v_add_f32_e32 v0, v66, v67
	v_cmp_lt_i32_e32 vcc, v228, v222
	v_add_f32_e32 v0, v0, v68
	v_add_f32_e32 v0, v0, v69
	v_cndmask_b32_e32 v66, v221, v228, vcc
	v_lshlrev_b32_e32 v66, 2, v66
	ds_bpermute_b32 v66, v66, v0
	v_cmp_lt_i32_e32 vcc, v227, v222
	v_mad_i64_i32 v[72:73], s[8:9], v88, s33, v[86:87]
	global_store_dwordx2 v[72:73], v[70:71], off sc0 sc1
	s_waitcnt lgkmcnt(0)
	v_add_f32_e32 v0, v0, v66
	v_cndmask_b32_e32 v66, v221, v227, vcc
	v_lshlrev_b32_e32 v66, 2, v66
	ds_bpermute_b32 v66, v66, v0
	v_cmp_lt_i32_e32 vcc, v226, v222
	s_waitcnt lgkmcnt(0)
	v_add_f32_e32 v0, v0, v66
	v_cndmask_b32_e32 v66, v221, v226, vcc
	v_lshlrev_b32_e32 v66, 2, v66
	ds_bpermute_b32 v66, v66, v0
	v_cmp_lt_i32_e32 vcc, v225, v222
	s_waitcnt lgkmcnt(0)
	v_add_f32_e32 v0, v0, v66
	v_cndmask_b32_e32 v66, v221, v225, vcc
	v_lshlrev_b32_e32 v66, 2, v66
	ds_bpermute_b32 v66, v66, v0
	v_cmp_lt_i32_e32 vcc, v217, v222
	s_waitcnt lgkmcnt(0)
	v_add_f32_e32 v0, v0, v66
	v_cndmask_b32_e32 v66, v221, v217, vcc
	v_lshlrev_b32_e32 v66, 2, v66
	ds_bpermute_b32 v66, v66, v0
	s_and_saveexec_b64 s[8:9], s[36:37]
	s_cbranch_execz .LBB0_90
	s_waitcnt lgkmcnt(0)
	v_add_f32_e32 v0, v0, v66
	v_lshlrev_b64 v[66:67], 5, v[88:89]
	v_lshl_add_u64 v[66:67], s[0:1], 0, v[66:67]
	global_store_dword v[66:67], v0, off sc0 sc1
	s_branch .LBB0_90

.LBB0_110:
	v_add_u32_e32 v0, s19, v131
	v_ashrrev_i32_e32 v36, 5, v0
	v_add_u32_e32 v4, 0x200, v0
	v_add_u32_e32 v32, s90, v36
	v_ashrrev_i32_e32 v35, 5, v4
	v_ashrrev_i32_e32 v33, 31, v32
	v_add_u32_e32 v28, s90, v35
	v_lshlrev_b64 v[40:41], 12, v[32:33]
	v_ashrrev_i32_e32 v29, 31, v28
	s_waitcnt lgkmcnt(0)
	v_lshl_add_u64 v[2:3], v[82:83], 0, v[40:41]
	v_lshlrev_b64 v[30:31], 12, v[28:29]
	v_lshl_add_u64 v[4:5], v[82:83], 0, v[30:31]
	global_load_dwordx4 v[14:17], v[2:3], off offset:512 nt
	global_load_dwordx4 v[10:13], v[4:5], off offset:512 nt
	v_add_u32_e32 v2, 0x400, v0
	v_add_u32_e32 v0, 0x600, v0
	v_ashrrev_i32_e32 v34, 5, v2
	v_ashrrev_i32_e32 v0, 5, v0
	v_add_u32_e32 v24, s90, v34
	v_add_u32_e32 v20, s90, v0
	v_ashrrev_i32_e32 v25, 31, v24
	v_ashrrev_i32_e32 v21, 31, v20
	v_lshlrev_b64 v[26:27], 12, v[24:25]
	v_lshlrev_b64 v[22:23], 12, v[20:21]
	v_lshl_add_u64 v[2:3], v[82:83], 0, v[26:27]
	v_lshl_add_u64 v[4:5], v[82:83], 0, v[22:23]
	global_load_dwordx4 v[6:9], v[2:3], off offset:512 nt
	s_nop 0
	global_load_dwordx4 v[2:5], v[4:5], off offset:512 nt
	v_lshlrev_b32_e32 v37, 9, v36
	v_xor_b32_e32 v36, v36, v131
	v_lshlrev_b32_e32 v36, 4, v36
	v_and_b32_e32 v36, 0x1f0, v36
	v_add3_u32 v36, 0, v37, v36
	ds_read_b128 v[36:39], v36
	v_lshl_add_u64 v[40:41], v[84:85], 0, v[40:41]
	s_and_b64 vcc, exec, s[38:39]
	s_waitcnt vmcnt(3) lgkmcnt(0)
	v_pk_add_f32 v[14:15], v[14:15], v[36:37]
	v_pk_add_f32 v[16:17], v[16:17], v[38:39]
	global_store_dwordx4 v[40:41], v[14:17], off offset:512 sc0 sc1
	s_cbranch_vccnz .LBB0_114
	v_cvt_pk_bf16_f32 v36, v14, v15
	v_pk_mul_f32 v[14:15], v[14:15], v[14:15]
	v_cvt_pk_bf16_f32 v37, v16, v17
	v_pk_mul_f32 v[16:17], v[16:17], v[16:17]
	v_add_f32_e32 v14, v14, v15
	v_cmp_lt_i32_e32 vcc, v228, v222
	v_add_f32_e32 v14, v14, v16
	v_add_f32_e32 v14, v14, v17
	v_cndmask_b32_e32 v15, v221, v228, vcc
	v_lshlrev_b32_e32 v15, 2, v15
	ds_bpermute_b32 v15, v15, v14
	v_cmp_lt_i32_e32 vcc, v227, v222
	v_mad_i64_i32 v[38:39], s[8:9], v32, s33, v[18:19]
	global_store_dwordx2 v[38:39], v[36:37], off offset:256 sc0 sc1
	s_waitcnt lgkmcnt(0)
	v_add_f32_e32 v14, v14, v15
	v_cndmask_b32_e32 v15, v221, v227, vcc
	v_lshlrev_b32_e32 v15, 2, v15
	ds_bpermute_b32 v15, v15, v14
	v_cmp_lt_i32_e32 vcc, v226, v222
	s_waitcnt lgkmcnt(0)
	v_add_f32_e32 v14, v14, v15
	v_cndmask_b32_e32 v15, v221, v226, vcc
	v_lshlrev_b32_e32 v15, 2, v15
	ds_bpermute_b32 v15, v15, v14
	v_cmp_lt_i32_e32 vcc, v225, v222
	s_waitcnt lgkmcnt(0)
	v_add_f32_e32 v14, v14, v15
	v_cndmask_b32_e32 v15, v221, v225, vcc
	v_lshlrev_b32_e32 v15, 2, v15
	ds_bpermute_b32 v15, v15, v14
	v_cmp_lt_i32_e32 vcc, v217, v222
	s_waitcnt lgkmcnt(0)
	v_add_f32_e32 v14, v14, v15
	v_cndmask_b32_e32 v15, v221, v217, vcc
	v_lshlrev_b32_e32 v15, 2, v15
	ds_bpermute_b32 v15, v15, v14
	s_and_saveexec_b64 s[8:9], s[36:37]
	s_cbranch_execz .LBB0_113
	s_waitcnt lgkmcnt(0)
	v_add_f32_e32 v16, v14, v15
	v_lshlrev_b64 v[14:15], 5, v[32:33]
	v_lshl_add_u64 v[14:15], s[0:1], 0, v[14:15]
	global_store_dword v[14:15], v16, off offset:4 sc0 sc1

.LBB0_114:
	s_waitcnt lgkmcnt(0)
	v_xor_b32_e32 v15, v35, v131
	v_lshlrev_b32_e32 v15, 4, v15
	v_lshlrev_b32_e32 v14, 9, v35
	v_and_b32_e32 v15, 0x1f0, v15
	v_add3_u32 v14, 0, v14, v15
	ds_read_b128 v[14:17], v14
	v_lshl_add_u64 v[30:31], v[84:85], 0, v[30:31]
	s_and_b64 vcc, exec, s[38:39]
	s_waitcnt vmcnt(3) lgkmcnt(0)
	v_pk_add_f32 v[10:11], v[10:11], v[14:15]
	v_pk_add_f32 v[12:13], v[12:13], v[16:17]
	global_store_dwordx4 v[30:31], v[10:13], off offset:512 sc0 sc1
	s_cbranch_vccnz .LBB0_118
	v_cvt_pk_bf16_f32 v14, v10, v11
	v_pk_mul_f32 v[10:11], v[10:11], v[10:11]
	v_cvt_pk_bf16_f32 v15, v12, v13
	v_pk_mul_f32 v[12:13], v[12:13], v[12:13]
	v_add_f32_e32 v10, v10, v11
	v_cmp_lt_i32_e32 vcc, v228, v222
	v_add_f32_e32 v10, v10, v12
	v_add_f32_e32 v10, v10, v13
	v_cndmask_b32_e32 v11, v221, v228, vcc
	v_lshlrev_b32_e32 v11, 2, v11
	ds_bpermute_b32 v11, v11, v10
	v_cmp_lt_i32_e32 vcc, v227, v222
	v_mad_i64_i32 v[16:17], s[8:9], v28, s33, v[18:19]
	global_store_dwordx2 v[16:17], v[14:15], off offset:256 sc0 sc1
	s_waitcnt lgkmcnt(0)
	v_add_f32_e32 v10, v10, v11
	v_cndmask_b32_e32 v11, v221, v227, vcc
	v_lshlrev_b32_e32 v11, 2, v11
	ds_bpermute_b32 v11, v11, v10
	v_cmp_lt_i32_e32 vcc, v226, v222
	s_waitcnt lgkmcnt(0)
	v_add_f32_e32 v10, v10, v11
	v_cndmask_b32_e32 v11, v221, v226, vcc
	v_lshlrev_b32_e32 v11, 2, v11
	ds_bpermute_b32 v11, v11, v10
	v_cmp_lt_i32_e32 vcc, v225, v222
	s_waitcnt lgkmcnt(0)
	v_add_f32_e32 v10, v10, v11
	v_cndmask_b32_e32 v11, v221, v225, vcc
	v_lshlrev_b32_e32 v11, 2, v11
	ds_bpermute_b32 v11, v11, v10
	v_cmp_lt_i32_e32 vcc, v217, v222
	s_waitcnt lgkmcnt(0)
	v_add_f32_e32 v10, v10, v11
	v_cndmask_b32_e32 v11, v221, v217, vcc
	v_lshlrev_b32_e32 v11, 2, v11
	ds_bpermute_b32 v11, v11, v10
	s_and_saveexec_b64 s[8:9], s[36:37]
	s_cbranch_execz .LBB0_117
	s_waitcnt lgkmcnt(0)
	v_add_f32_e32 v12, v10, v11
	v_lshlrev_b64 v[10:11], 5, v[28:29]
	v_lshl_add_u64 v[10:11], s[0:1], 0, v[10:11]
	global_store_dword v[10:11], v12, off offset:4 sc0 sc1

.LBB0_118:
	s_waitcnt lgkmcnt(0)
	v_xor_b32_e32 v11, v34, v131
	v_lshlrev_b32_e32 v11, 4, v11
	v_lshlrev_b32_e32 v10, 9, v34
	v_and_b32_e32 v11, 0x1f0, v11
	v_add3_u32 v10, 0, v10, v11
	ds_read_b128 v[10:13], v10
	v_lshl_add_u64 v[14:15], v[84:85], 0, v[26:27]
	s_and_b64 vcc, exec, s[38:39]
	s_waitcnt vmcnt(3) lgkmcnt(0)
	v_pk_add_f32 v[6:7], v[6:7], v[10:11]
	v_pk_add_f32 v[8:9], v[8:9], v[12:13]
	global_store_dwordx4 v[14:15], v[6:9], off offset:512 sc0 sc1
	s_cbranch_vccnz .LBB0_122
	v_cvt_pk_bf16_f32 v10, v6, v7
	v_pk_mul_f32 v[6:7], v[6:7], v[6:7]
	v_cvt_pk_bf16_f32 v11, v8, v9
	v_pk_mul_f32 v[8:9], v[8:9], v[8:9]
	v_add_f32_e32 v6, v6, v7
	v_cmp_lt_i32_e32 vcc, v228, v222
	v_add_f32_e32 v6, v6, v8
	v_add_f32_e32 v6, v6, v9
	v_cndmask_b32_e32 v7, v221, v228, vcc
	v_lshlrev_b32_e32 v7, 2, v7
	ds_bpermute_b32 v7, v7, v6
	v_cmp_lt_i32_e32 vcc, v227, v222
	v_mad_i64_i32 v[12:13], s[8:9], v24, s33, v[18:19]
	global_store_dwordx2 v[12:13], v[10:11], off offset:256 sc0 sc1
	s_waitcnt lgkmcnt(0)
	v_add_f32_e32 v6, v6, v7
	v_cndmask_b32_e32 v7, v221, v227, vcc
	v_lshlrev_b32_e32 v7, 2, v7
	ds_bpermute_b32 v7, v7, v6
	v_cmp_lt_i32_e32 vcc, v226, v222
	s_waitcnt lgkmcnt(0)
	v_add_f32_e32 v6, v6, v7
	v_cndmask_b32_e32 v7, v221, v226, vcc
	v_lshlrev_b32_e32 v7, 2, v7
	ds_bpermute_b32 v7, v7, v6
	v_cmp_lt_i32_e32 vcc, v225, v222
	s_waitcnt lgkmcnt(0)
	v_add_f32_e32 v6, v6, v7
	v_cndmask_b32_e32 v7, v221, v225, vcc
	v_lshlrev_b32_e32 v7, 2, v7
	ds_bpermute_b32 v7, v7, v6
	v_cmp_lt_i32_e32 vcc, v217, v222
	s_waitcnt lgkmcnt(0)
	v_add_f32_e32 v6, v6, v7
	v_cndmask_b32_e32 v7, v221, v217, vcc
	v_lshlrev_b32_e32 v7, 2, v7
	ds_bpermute_b32 v7, v7, v6
	s_and_saveexec_b64 s[8:9], s[36:37]
	s_cbranch_execz .LBB0_121
	s_waitcnt lgkmcnt(0)
	v_add_f32_e32 v8, v6, v7
	v_lshlrev_b64 v[6:7], 5, v[24:25]
	v_lshl_add_u64 v[6:7], s[0:1], 0, v[6:7]
	global_store_dword v[6:7], v8, off offset:4 sc0 sc1

.LBB0_122:
	s_nop 0
	v_lshlrev_b32_e32 v6, 9, v0
	v_xor_b32_e32 v0, v0, v131
	v_lshlrev_b32_e32 v0, 4, v0
	v_and_b32_e32 v0, 0x1f0, v0
	v_add3_u32 v0, 0, v6, v0
	s_waitcnt lgkmcnt(0)
	ds_read_b128 v[6:9], v0
	v_lshl_add_u64 v[10:11], v[84:85], 0, v[22:23]
	s_and_b64 vcc, exec, s[38:39]
	s_waitcnt vmcnt(3) lgkmcnt(0)
	v_pk_add_f32 v[2:3], v[2:3], v[6:7]
	v_pk_add_f32 v[4:5], v[4:5], v[8:9]
	global_store_dwordx4 v[10:11], v[2:5], off offset:512 sc0 sc1
	s_cbranch_vccnz .LBB0_109
	v_cvt_pk_bf16_f32 v6, v2, v3
	v_pk_mul_f32 v[2:3], v[2:3], v[2:3]
	v_cvt_pk_bf16_f32 v7, v4, v5
	v_pk_mul_f32 v[4:5], v[4:5], v[4:5]
	v_add_f32_e32 v0, v2, v3
	v_cmp_lt_i32_e32 vcc, v228, v222
	v_add_f32_e32 v0, v0, v4
	v_add_f32_e32 v0, v0, v5
	v_cndmask_b32_e32 v2, v221, v228, vcc
	v_lshlrev_b32_e32 v2, 2, v2
	ds_bpermute_b32 v2, v2, v0
	v_cmp_lt_i32_e32 vcc, v227, v222
	v_mad_i64_i32 v[8:9], s[8:9], v20, s33, v[18:19]
	global_store_dwordx2 v[8:9], v[6:7], off offset:256 sc0 sc1
	s_waitcnt lgkmcnt(0)
	v_add_f32_e32 v0, v0, v2
	v_cndmask_b32_e32 v2, v221, v227, vcc
	v_lshlrev_b32_e32 v2, 2, v2
	ds_bpermute_b32 v2, v2, v0
	v_cmp_lt_i32_e32 vcc, v226, v222
	s_waitcnt lgkmcnt(0)
	v_add_f32_e32 v0, v0, v2
	v_cndmask_b32_e32 v2, v221, v226, vcc
	v_lshlrev_b32_e32 v2, 2, v2
	ds_bpermute_b32 v2, v2, v0
	v_cmp_lt_i32_e32 vcc, v225, v222
	s_waitcnt lgkmcnt(0)
	v_add_f32_e32 v0, v0, v2
	v_cndmask_b32_e32 v2, v221, v225, vcc
	v_lshlrev_b32_e32 v2, 2, v2
	ds_bpermute_b32 v2, v2, v0
	v_cmp_lt_i32_e32 vcc, v217, v222
	s_waitcnt lgkmcnt(0)
	v_add_f32_e32 v0, v0, v2
	v_cndmask_b32_e32 v2, v221, v217, vcc
	v_lshlrev_b32_e32 v2, 2, v2
	ds_bpermute_b32 v2, v2, v0
	s_and_saveexec_b64 s[8:9], s[36:37]
	s_cbranch_execz .LBB0_108
	s_waitcnt lgkmcnt(0)
	v_add_f32_e32 v0, v0, v2
	v_lshlrev_b64 v[2:3], 5, v[20:21]
	v_lshl_add_u64 v[2:3], s[0:1], 0, v[2:3]
	global_store_dword v[2:3], v0, off offset:4 sc0 sc1
	s_branch .LBB0_108

.Lb_fast:
	v_readlane_b32 s18, v253, 39
	s_cmp_lg_u32 s18, 0
	s_cselect_b32 s42, s21, s43
	s_lshl_b32 s42, s42, 8
	v_readlane_b32 s18, v254, 36
	s_or_b32 s42, s42, s18
	v_and_b32_e32 v231, 31, v221
	v_lshrrev_b32_e32 v229, 5, v221
	v_lshlrev_b32_e32 v229, 3, v229
	v_sub_u32_e32 v231, v231, v229
	v_mov_b32_e32 v218, 0xf149f2ca
.Lb_top:
	s_bitcmp1_b32 s95, 0
	s_cbranch_scc1 .Lb_nobar
	s_waitcnt vmcnt(0)
	s_barrier
	s_cmp_ge_u32 s95, s78
	s_cbranch_scc1 .Lb_nodma
	s_add_i32 s18, s25, 0xffff4000
	s_andn2_b32 s22, 0x8000, s18
	v_lshl_add_u64 v[98:99], v[148:149], 0, v[0:1]
	s_mov_b64 s[18:19], 0x4400c00
	v_add_u32_e32 v104, s22, v152
	v_lshl_add_u64 v[100:101], v[98:99], 0, s[18:19]
	v_readfirstlane_b32 s18, v104
	s_mov_b32 m0, s18
	s_mov_b64 s[18:19], 0x11e40000
	global_load_lds_dwordx4 v[100:101], off
	v_lshl_add_u64 v[100:101], v[146:147], 0, v[0:1]
	v_add_u32_e32 v104, 0x2000, v104
	v_lshl_add_u64 v[102:103], v[100:101], 0, s[18:19]
	v_readfirstlane_b32 s18, v104
	s_mov_b32 m0, s18
	s_add_i32 s18, s95, 1
	global_load_lds_dwordx4 v[102:103], off
	s_cmp_ge_u32 s18, s78
	s_cbranch_scc1 .Lb_nodma
	s_and_b32 s22, s25, 0xc000
	s_mov_b64 s[18:19], 0x4453c00
	v_add_u32_e32 v102, s22, v152
	v_lshl_add_u64 v[98:99], v[98:99], 0, s[18:19]
	v_readfirstlane_b32 s18, v102
	s_mov_b32 m0, s18
	s_mov_b64 s[18:19], 0x11e40080
	global_load_lds_dwordx4 v[98:99], off
	v_lshl_add_u64 v[98:99], v[100:101], 0, s[18:19]
	v_add_u32_e32 v100, 0x2000, v102
	s_nop 0
	v_readfirstlane_b32 s18, v100
	s_mov_b32 m0, s18
	s_nop 0
	global_load_lds_dwordx4 v[98:99], off
.Lb_nodma:
.Lb_nobar:
	s_add_i32 s18, s25, 0xffff4000
	s_and_b32 s24, s18, 0xc000
	s_sub_i32 s18, s94, s42
	s_cmp_eq_u32 s18, 0xffffff80
	s_cbranch_scc1 .Lb_em2
	s_cmp_eq_u32 s18, 0x80
	s_cbranch_scc1 .Lb_ep2
	s_add_i32 s18, s18, 64
	s_cmp_gt_u32 s18, 0x80
	s_cbranch_scc1 .Lb_next
.Lb_efull:
	v_add_u32_e32 v219, s24, v153
	v_add_u32_e32 v220, s24, v154
	v_add_u32_e32 v223, s24, v155
	v_add_u32_e32 v224, s24, v156
	ds_read_b128 v[194:197], v219
	ds_read_b128 v[198:201], v220
	ds_read_b128 v[202:205], v223
	ds_read_b128 v[206:209], v224
	s_waitcnt lgkmcnt(0)
	v_mfma_f32_32x32x16_bf16 v[98:113], v[194:197], v[114:117], v[82:97]
	v_mfma_f32_32x32x16_bf16 v[98:113], v[198:201], v[122:125], v[98:113]
	v_mfma_f32_32x32x16_bf16 v[98:113], v[202:205], v[118:121], v[98:113]
	v_mfma_f32_32x32x16_bf16 v[98:113], v[206:209], v[126:129], v[98:113]
	v_add_u32_e32 v248, s24, v158
	ds_read_b128 v[164:167], v248 offset:8192
	ds_read_b128 v[168:171], v248 offset:12288
	v_add_u32_e32 v248, s24, v159
	ds_read_b128 v[232:235], v248 offset:8192
	ds_read_b128 v[236:239], v248 offset:12288
	s_nop 5
	v_max_f32_e32 v229, v98, v99
	v_max3_f32 v229, v229, v100, v101
	v_max3_f32 v229, v229, v102, v103
	v_max3_f32 v229, v229, v104, v105
	v_max3_f32 v229, v229, v106, v107
	v_max3_f32 v229, v229, v108, v109
	v_max3_f32 v229, v229, v110, v111
	v_max3_f32 v229, v229, v112, v113
	v_mov_b32_e32 v230, v229
	s_nop 1
	v_permlane32_swap_b32_e32 v229, v230
	v_max_f32_e32 v229, v229, v230
	v_cmp_lt_f32_e32 vcc, s3, v229
	s_cbranch_vccnz .Lb_resc_f_0
.Lb_resc_f_0_ret:
	v_mfma_f32_32x32x16_bf16 v[178:193], v[194:197], v[130:133], v[66:81]
	v_exp_f32_e32 v98, v98
	v_exp_f32_e32 v99, v99
	v_exp_f32_e32 v100, v100
	v_exp_f32_e32 v101, v101
	v_add_f32_e32 v229, v99, v98
	v_exp_f32_e32 v102, v102
	v_add_f32_e32 v229, v100, v229
	v_mfma_f32_32x32x16_bf16 v[178:193], v[198:201], v[138:141], v[178:193]
	v_exp_f32_e32 v103, v103
	v_add_f32_e32 v229, v101, v229
	v_exp_f32_e32 v104, v104
	v_add_f32_e32 v229, v102, v229
	v_exp_f32_e32 v105, v105
	v_add_f32_e32 v229, v103, v229
	v_cvt_pk_bf16_f32 v98, v98, v99
	v_mfma_f32_32x32x16_bf16 v[178:193], v[202:205], v[134:137], v[178:193]
	v_exp_f32_e32 v106, v106
	v_add_f32_e32 v229, v104, v229
	v_cvt_pk_bf16_f32 v99, v100, v101
	v_exp_f32_e32 v107, v107
	v_add_f32_e32 v229, v105, v229
	v_cvt_pk_bf16_f32 v100, v102, v103
	v_exp_f32_e32 v108, v108
	v_mfma_f32_32x32x16_bf16 v[178:193], v[206:209], v[142:145], v[178:193]
	v_add_f32_e32 v229, v106, v229
	v_cvt_pk_bf16_f32 v101, v104, v105
	v_exp_f32_e32 v109, v109
	v_add_f32_e32 v229, v107, v229
	v_exp_f32_e32 v110, v110
	v_add_f32_e32 v229, v108, v229
	v_exp_f32_e32 v111, v111
	v_add_f32_e32 v229, v109, v229
	v_exp_f32_e32 v112, v112
	v_add_f32_e32 v229, v110, v229
	v_exp_f32_e32 v113, v113
	v_add_f32_e32 v229, v111, v229
	v_cvt_pk_bf16_f32 v102, v106, v107
	v_add_f32_e32 v229, v112, v229
	v_cvt_pk_bf16_f32 v103, v108, v109
	v_add_f32_e32 v229, v113, v229
	v_cvt_pk_bf16_f32 v104, v110, v111
	v_add_f32_e32 v151, v151, v229
	v_cvt_pk_bf16_f32 v105, v112, v113
	s_waitcnt lgkmcnt(0)
	ds_read_b128 v[194:197], v219 offset:4096
	ds_read_b128 v[198:201], v220 offset:4096
	ds_read_b128 v[202:205], v223 offset:4096
	ds_read_b128 v[206:209], v224 offset:4096
	v_mfma_f32_32x32x16_bf16 v[50:65], v[164:167], v[98:101], v[50:65]
	v_max_f32_e32 v229, v178, v179
	v_max3_f32 v229, v229, v180, v181
	v_mfma_f32_32x32x16_bf16 v[34:49], v[168:171], v[98:101], v[34:49]
	v_max3_f32 v229, v229, v182, v183
	v_max3_f32 v229, v229, v184, v185
	v_max3_f32 v229, v229, v186, v187
	v_mfma_f32_32x32x16_bf16 v[50:65], v[232:235], v[102:105], v[50:65]
	v_max3_f32 v229, v229, v188, v189
	v_max3_f32 v229, v229, v190, v191
	v_max3_f32 v229, v229, v192, v193
	v_mfma_f32_32x32x16_bf16 v[34:49], v[236:239], v[102:105], v[34:49]
	v_mov_b32_e32 v230, v229
	s_nop 1
	v_permlane32_swap_b32_e32 v229, v230
	v_max_f32_e32 v229, v229, v230
	v_cmp_lt_f32_e32 vcc, s3, v229
	s_cbranch_vccnz .Lb_resc_f_1
.Lb_resc_f_1_ret:
	s_waitcnt lgkmcnt(0)
	v_mfma_f32_32x32x16_bf16 v[98:113], v[194:197], v[114:117], v[82:97]
	v_exp_f32_e32 v178, v178
	v_exp_f32_e32 v179, v179
	v_exp_f32_e32 v180, v180
	v_exp_f32_e32 v181, v181
	v_add_f32_e32 v229, v179, v178
	v_exp_f32_e32 v182, v182
	v_add_f32_e32 v229, v180, v229
	v_mfma_f32_32x32x16_bf16 v[98:113], v[198:201], v[122:125], v[98:113]
	v_exp_f32_e32 v183, v183
	v_add_f32_e32 v229, v181, v229
	v_exp_f32_e32 v184, v184
	v_add_f32_e32 v229, v182, v229
	v_exp_f32_e32 v185, v185
	v_add_f32_e32 v229, v183, v229
	v_cvt_pk_bf16_f32 v178, v178, v179
	v_mfma_f32_32x32x16_bf16 v[98:113], v[202:205], v[118:121], v[98:113]
	v_exp_f32_e32 v186, v186
	v_add_f32_e32 v229, v184, v229
	v_cvt_pk_bf16_f32 v179, v180, v181
	v_exp_f32_e32 v187, v187
	v_add_f32_e32 v229, v185, v229
	v_cvt_pk_bf16_f32 v180, v182, v183
	v_exp_f32_e32 v188, v188
	v_mfma_f32_32x32x16_bf16 v[98:113], v[206:209], v[126:129], v[98:113]
	v_add_f32_e32 v229, v186, v229
	v_cvt_pk_bf16_f32 v181, v184, v185
	v_exp_f32_e32 v189, v189
	v_add_f32_e32 v229, v187, v229
	v_exp_f32_e32 v190, v190
	v_add_f32_e32 v229, v188, v229
	v_exp_f32_e32 v191, v191
	v_add_f32_e32 v229, v189, v229
	v_exp_f32_e32 v192, v192
	v_add_f32_e32 v229, v190, v229
	v_exp_f32_e32 v193, v193
	v_add_f32_e32 v229, v191, v229
	v_cvt_pk_bf16_f32 v182, v186, v187
	v_add_f32_e32 v229, v192, v229
	v_cvt_pk_bf16_f32 v183, v188, v189
	v_add_f32_e32 v229, v193, v229
	v_cvt_pk_bf16_f32 v184, v190, v191
	v_add_f32_e32 v150, v150, v229
	v_cvt_pk_bf16_f32 v185, v192, v193
	v_mfma_f32_32x32x16_bf16 v[18:33], v[164:167], v[178:181], v[18:33]
	v_max_f32_e32 v229, v98, v99
	v_max3_f32 v229, v229, v100, v101
	v_mfma_f32_32x32x16_bf16 v[2:17], v[168:171], v[178:181], v[2:17]
	v_max3_f32 v229, v229, v102, v103
	v_max3_f32 v229, v229, v104, v105
	v_max3_f32 v229, v229, v106, v107
	v_mfma_f32_32x32x16_bf16 v[18:33], v[232:235], v[182:185], v[18:33]
	v_max3_f32 v229, v229, v108, v109
	v_max3_f32 v229, v229, v110, v111
	v_max3_f32 v229, v229, v112, v113
	v_mfma_f32_32x32x16_bf16 v[2:17], v[236:239], v[182:185], v[2:17]
	v_add_u32_e32 v248, s24, v160
	ds_read_b128 v[164:167], v248 offset:8192
	ds_read_b128 v[168:171], v248 offset:12288
	v_add_u32_e32 v248, s24, v161
	ds_read_b128 v[232:235], v248 offset:8192
	ds_read_b128 v[236:239], v248 offset:12288
	v_mov_b32_e32 v230, v229
	s_nop 1
	v_permlane32_swap_b32_e32 v229, v230
	v_max_f32_e32 v229, v229, v230
	v_cmp_lt_f32_e32 vcc, s3, v229
	s_cbranch_vccnz .Lb_resc_f_2
.Lb_resc_f_2_ret:
	v_mfma_f32_32x32x16_bf16 v[178:193], v[194:197], v[130:133], v[66:81]
	v_exp_f32_e32 v98, v98
	v_exp_f32_e32 v99, v99
	v_exp_f32_e32 v100, v100
	v_exp_f32_e32 v101, v101
	v_add_f32_e32 v229, v99, v98
	v_exp_f32_e32 v102, v102
	v_add_f32_e32 v229, v100, v229
	v_mfma_f32_32x32x16_bf16 v[178:193], v[198:201], v[138:141], v[178:193]
	v_exp_f32_e32 v103, v103
	v_add_f32_e32 v229, v101, v229
	v_exp_f32_e32 v104, v104
	v_add_f32_e32 v229, v102, v229
	v_exp_f32_e32 v105, v105
	v_add_f32_e32 v229, v103, v229
	v_cvt_pk_bf16_f32 v98, v98, v99
	v_mfma_f32_32x32x16_bf16 v[178:193], v[202:205], v[134:137], v[178:193]
	v_exp_f32_e32 v106, v106
	v_add_f32_e32 v229, v104, v229
	v_cvt_pk_bf16_f32 v99, v100, v101
	v_exp_f32_e32 v107, v107
	v_add_f32_e32 v229, v105, v229
	v_cvt_pk_bf16_f32 v100, v102, v103
	v_exp_f32_e32 v108, v108
	v_mfma_f32_32x32x16_bf16 v[178:193], v[206:209], v[142:145], v[178:193]
	v_add_f32_e32 v229, v106, v229
	v_cvt_pk_bf16_f32 v101, v104, v105
	v_exp_f32_e32 v109, v109
	v_add_f32_e32 v229, v107, v229
	v_exp_f32_e32 v110, v110
	v_add_f32_e32 v229, v108, v229
	v_exp_f32_e32 v111, v111
	v_add_f32_e32 v229, v109, v229
	v_exp_f32_e32 v112, v112
	v_add_f32_e32 v229, v110, v229
	v_exp_f32_e32 v113, v113
	v_add_f32_e32 v229, v111, v229
	v_cvt_pk_bf16_f32 v102, v106, v107
	v_add_f32_e32 v229, v112, v229
	v_cvt_pk_bf16_f32 v103, v108, v109
	v_add_f32_e32 v229, v113, v229
	v_cvt_pk_bf16_f32 v104, v110, v111
	v_add_f32_e32 v151, v151, v229
	v_cvt_pk_bf16_f32 v105, v112, v113
	s_waitcnt lgkmcnt(0)
	v_mfma_f32_32x32x16_bf16 v[50:65], v[164:167], v[98:101], v[50:65]
	v_max_f32_e32 v229, v178, v179
	v_max3_f32 v229, v229, v180, v181
	v_mfma_f32_32x32x16_bf16 v[34:49], v[168:171], v[98:101], v[34:49]
	v_max3_f32 v229, v229, v182, v183
	v_max3_f32 v229, v229, v184, v185
	v_max3_f32 v229, v229, v186, v187
	v_mfma_f32_32x32x16_bf16 v[50:65], v[232:235], v[102:105], v[50:65]
	v_max3_f32 v229, v229, v188, v189
	v_max3_f32 v229, v229, v190, v191
	v_max3_f32 v229, v229, v192, v193
	v_mfma_f32_32x32x16_bf16 v[34:49], v[236:239], v[102:105], v[34:49]
	v_mov_b32_e32 v230, v229
	s_nop 1
	v_permlane32_swap_b32_e32 v229, v230
	v_max_f32_e32 v229, v229, v230
	v_cmp_lt_f32_e32 vcc, s3, v229
	s_cbranch_vccnz .Lb_resc_f_3
.Lb_resc_f_3_ret:
	v_exp_f32_e32 v178, v178
	v_exp_f32_e32 v179, v179
	v_exp_f32_e32 v180, v180
	v_exp_f32_e32 v181, v181
	v_add_f32_e32 v229, v179, v178
	v_exp_f32_e32 v182, v182
	v_add_f32_e32 v229, v180, v229
	v_exp_f32_e32 v183, v183
	v_add_f32_e32 v229, v181, v229
	v_exp_f32_e32 v184, v184
	v_add_f32_e32 v229, v182, v229
	v_exp_f32_e32 v185, v185
	v_add_f32_e32 v229, v183, v229
	v_cvt_pk_bf16_f32 v178, v178, v179
	v_exp_f32_e32 v186, v186
	v_add_f32_e32 v229, v184, v229
	v_cvt_pk_bf16_f32 v179, v180, v181
	v_exp_f32_e32 v187, v187
	v_add_f32_e32 v229, v185, v229
	v_cvt_pk_bf16_f32 v180, v182, v183
	v_exp_f32_e32 v188, v188
	v_add_f32_e32 v229, v186, v229
	v_cvt_pk_bf16_f32 v181, v184, v185
	v_exp_f32_e32 v189, v189
	v_add_f32_e32 v229, v187, v229
	v_exp_f32_e32 v190, v190
	v_add_f32_e32 v229, v188, v229
	v_exp_f32_e32 v191, v191
	v_add_f32_e32 v229, v189, v229
	v_exp_f32_e32 v192, v192
	v_add_f32_e32 v229, v190, v229
	v_exp_f32_e32 v193, v193
	v_add_f32_e32 v229, v191, v229
	v_cvt_pk_bf16_f32 v182, v186, v187
	v_add_f32_e32 v229, v192, v229
	v_cvt_pk_bf16_f32 v183, v188, v189
	v_add_f32_e32 v229, v193, v229
	v_cvt_pk_bf16_f32 v184, v190, v191
	v_add_f32_e32 v150, v150, v229
	v_cvt_pk_bf16_f32 v185, v192, v193
	v_mfma_f32_32x32x16_bf16 v[18:33], v[164:167], v[178:181], v[18:33]
	v_mfma_f32_32x32x16_bf16 v[2:17], v[168:171], v[178:181], v[2:17]
	v_mfma_f32_32x32x16_bf16 v[18:33], v[232:235], v[182:185], v[18:33]
	v_mfma_f32_32x32x16_bf16 v[2:17], v[236:239], v[182:185], v[2:17]
	s_branch .Lb_next
.Lb_em2:
	v_add_u32_e32 v219, s24, v153
	v_add_u32_e32 v220, s24, v154
	v_add_u32_e32 v223, s24, v155
	v_add_u32_e32 v224, s24, v156
	ds_read_b128 v[194:197], v219
	ds_read_b128 v[198:201], v220
	ds_read_b128 v[202:205], v223
	ds_read_b128 v[206:209], v224
	s_waitcnt lgkmcnt(0)
	v_mfma_f32_32x32x16_bf16 v[98:113], v[194:197], v[114:117], v[82:97]
	v_mfma_f32_32x32x16_bf16 v[98:113], v[198:201], v[122:125], v[98:113]
	v_mfma_f32_32x32x16_bf16 v[98:113], v[202:205], v[118:121], v[98:113]
	v_mfma_f32_32x32x16_bf16 v[98:113], v[206:209], v[126:129], v[98:113]
	v_add_u32_e32 v248, s24, v158
	ds_read_b128 v[164:167], v248 offset:8192
	ds_read_b128 v[168:171], v248 offset:12288
	v_add_u32_e32 v248, s24, v159
	ds_read_b128 v[232:235], v248 offset:8192
	ds_read_b128 v[236:239], v248 offset:12288
	ds_read_b128 v[194:197], v219 offset:4096
	ds_read_b128 v[198:201], v220 offset:4096
	ds_read_b128 v[202:205], v223 offset:4096
	ds_read_b128 v[206:209], v224 offset:4096
	s_nop 1
	v_cmp_lt_i32_e32 vcc, 0, v231
	s_nop 1
	v_cndmask_b32_e32 v98, v98, v218, vcc
	v_cmp_lt_i32_e32 vcc, 1, v231
	s_nop 1
	v_cndmask_b32_e32 v99, v99, v218, vcc
	v_cmp_lt_i32_e32 vcc, 2, v231
	s_nop 1
	v_cndmask_b32_e32 v100, v100, v218, vcc
	v_cmp_lt_i32_e32 vcc, 3, v231
	s_nop 1
	v_cndmask_b32_e32 v101, v101, v218, vcc
	v_cmp_lt_i32_e32 vcc, 4, v231
	s_nop 1
	v_cndmask_b32_e32 v102, v102, v218, vcc
	v_cmp_lt_i32_e32 vcc, 5, v231
	s_nop 1
	v_cndmask_b32_e32 v103, v103, v218, vcc
	v_cmp_lt_i32_e32 vcc, 6, v231
	s_nop 1
	v_cndmask_b32_e32 v104, v104, v218, vcc
	v_cmp_lt_i32_e32 vcc, 7, v231
	s_nop 1
	v_cndmask_b32_e32 v105, v105, v218, vcc
	v_cmp_lt_i32_e32 vcc, 16, v231
	s_nop 1
	v_cndmask_b32_e32 v106, v106, v218, vcc
	v_cmp_lt_i32_e32 vcc, 17, v231
	s_nop 1
	v_cndmask_b32_e32 v107, v107, v218, vcc
	v_cmp_lt_i32_e32 vcc, 18, v231
	s_nop 1
	v_cndmask_b32_e32 v108, v108, v218, vcc
	v_cmp_lt_i32_e32 vcc, 19, v231
	s_nop 1
	v_cndmask_b32_e32 v109, v109, v218, vcc
	v_cmp_lt_i32_e32 vcc, 20, v231
	s_nop 1
	v_cndmask_b32_e32 v110, v110, v218, vcc
	v_cmp_lt_i32_e32 vcc, 21, v231
	s_nop 1
	v_cndmask_b32_e32 v111, v111, v218, vcc
	v_cmp_lt_i32_e32 vcc, 22, v231
	s_nop 1
	v_cndmask_b32_e32 v112, v112, v218, vcc
	v_cmp_lt_i32_e32 vcc, 23, v231
	s_nop 1
	v_cndmask_b32_e32 v113, v113, v218, vcc
	v_max_f32_e32 v229, v98, v99
	v_max3_f32 v229, v229, v100, v101
	v_max3_f32 v229, v229, v102, v103
	v_max3_f32 v229, v229, v104, v105
	v_max3_f32 v229, v229, v106, v107
	v_max3_f32 v229, v229, v108, v109
	v_max3_f32 v229, v229, v110, v111
	v_max3_f32 v229, v229, v112, v113
	v_mov_b32_e32 v230, v229
	s_nop 1
	v_permlane32_swap_b32_e32 v229, v230
	v_max_f32_e32 v229, v229, v230
	v_cmp_lt_f32_e32 vcc, s3, v229
	s_cbranch_vccnz .Lb_resc_m_0
.Lb_resc_m_0_ret:
	s_waitcnt lgkmcnt(0)
	v_mfma_f32_32x32x16_bf16 v[178:193], v[194:197], v[114:117], v[82:97]
	v_exp_f32_e32 v98, v98
	v_exp_f32_e32 v99, v99
	v_exp_f32_e32 v100, v100
	v_exp_f32_e32 v101, v101
	v_add_f32_e32 v229, v99, v98
	v_exp_f32_e32 v102, v102
	v_add_f32_e32 v229, v100, v229
	v_mfma_f32_32x32x16_bf16 v[178:193], v[198:201], v[122:125], v[178:193]
	v_exp_f32_e32 v103, v103
	v_add_f32_e32 v229, v101, v229
	v_exp_f32_e32 v104, v104
	v_add_f32_e32 v229, v102, v229
	v_exp_f32_e32 v105, v105
	v_add_f32_e32 v229, v103, v229
	v_cvt_pk_bf16_f32 v98, v98, v99
	v_mfma_f32_32x32x16_bf16 v[178:193], v[202:205], v[118:121], v[178:193]
	v_exp_f32_e32 v106, v106
	v_add_f32_e32 v229, v104, v229
	v_cvt_pk_bf16_f32 v99, v100, v101
	v_exp_f32_e32 v107, v107
	v_add_f32_e32 v229, v105, v229
	v_cvt_pk_bf16_f32 v100, v102, v103
	v_exp_f32_e32 v108, v108
	v_mfma_f32_32x32x16_bf16 v[178:193], v[206:209], v[126:129], v[178:193]
	v_add_f32_e32 v229, v106, v229
	v_cvt_pk_bf16_f32 v101, v104, v105
	v_exp_f32_e32 v109, v109
	v_add_f32_e32 v229, v107, v229
	v_exp_f32_e32 v110, v110
	v_add_f32_e32 v229, v108, v229
	v_exp_f32_e32 v111, v111
	v_add_f32_e32 v229, v109, v229
	v_exp_f32_e32 v112, v112
	v_add_f32_e32 v229, v110, v229
	v_exp_f32_e32 v113, v113
	v_add_f32_e32 v229, v111, v229
	v_cvt_pk_bf16_f32 v102, v106, v107
	v_add_f32_e32 v229, v112, v229
	v_cvt_pk_bf16_f32 v103, v108, v109
	v_add_f32_e32 v229, v113, v229
	v_cvt_pk_bf16_f32 v104, v110, v111
	v_add_f32_e32 v151, v151, v229
	v_cvt_pk_bf16_f32 v105, v112, v113
	v_mfma_f32_32x32x16_bf16 v[50:65], v[164:167], v[98:101], v[50:65]
	v_max_f32_e32 v229, v178, v179
	v_max3_f32 v229, v229, v180, v181
	v_mfma_f32_32x32x16_bf16 v[34:49], v[168:171], v[98:101], v[34:49]
	v_max3_f32 v229, v229, v182, v183
	v_max3_f32 v229, v229, v184, v185
	v_max3_f32 v229, v229, v186, v187
	v_mfma_f32_32x32x16_bf16 v[50:65], v[232:235], v[102:105], v[50:65]
	v_max3_f32 v229, v229, v188, v189
	v_max3_f32 v229, v229, v190, v191
	v_max3_f32 v229, v229, v192, v193
	v_mfma_f32_32x32x16_bf16 v[34:49], v[236:239], v[102:105], v[34:49]
	v_add_u32_e32 v248, s24, v160
	ds_read_b128 v[164:167], v248 offset:8192
	ds_read_b128 v[168:171], v248 offset:12288
	v_add_u32_e32 v248, s24, v161
	ds_read_b128 v[232:235], v248 offset:8192
	ds_read_b128 v[236:239], v248 offset:12288
	v_mov_b32_e32 v230, v229
	s_nop 1
	v_permlane32_swap_b32_e32 v229, v230
	v_max_f32_e32 v229, v229, v230
	v_cmp_lt_f32_e32 vcc, s3, v229
	s_cbranch_vccnz .Lb_resc_m_1
.Lb_resc_m_1_ret:
	v_mfma_f32_32x32x16_bf16 v[98:113], v[194:197], v[130:133], v[66:81]
	v_exp_f32_e32 v178, v178
	v_exp_f32_e32 v179, v179
	v_exp_f32_e32 v180, v180
	v_exp_f32_e32 v181, v181
	v_add_f32_e32 v229, v179, v178
	v_exp_f32_e32 v182, v182
	v_add_f32_e32 v229, v180, v229
	v_mfma_f32_32x32x16_bf16 v[98:113], v[198:201], v[138:141], v[98:113]
	v_exp_f32_e32 v183, v183
	v_add_f32_e32 v229, v181, v229
	v_exp_f32_e32 v184, v184
	v_add_f32_e32 v229, v182, v229
	v_exp_f32_e32 v185, v185
	v_add_f32_e32 v229, v183, v229
	v_cvt_pk_bf16_f32 v178, v178, v179
	v_mfma_f32_32x32x16_bf16 v[98:113], v[202:205], v[134:137], v[98:113]
	v_exp_f32_e32 v186, v186
	v_add_f32_e32 v229, v184, v229
	v_cvt_pk_bf16_f32 v179, v180, v181
	v_exp_f32_e32 v187, v187
	v_add_f32_e32 v229, v185, v229
	v_cvt_pk_bf16_f32 v180, v182, v183
	v_exp_f32_e32 v188, v188
	v_mfma_f32_32x32x16_bf16 v[98:113], v[206:209], v[142:145], v[98:113]
	v_add_f32_e32 v229, v186, v229
	v_cvt_pk_bf16_f32 v181, v184, v185
	v_exp_f32_e32 v189, v189
	v_add_f32_e32 v229, v187, v229
	v_exp_f32_e32 v190, v190
	v_add_f32_e32 v229, v188, v229
	v_exp_f32_e32 v191, v191
	v_add_f32_e32 v229, v189, v229
	v_exp_f32_e32 v192, v192
	v_add_f32_e32 v229, v190, v229
	v_exp_f32_e32 v193, v193
	v_add_f32_e32 v229, v191, v229
	v_cvt_pk_bf16_f32 v182, v186, v187
	v_add_f32_e32 v229, v192, v229
	v_cvt_pk_bf16_f32 v183, v188, v189
	v_add_f32_e32 v229, v193, v229
	v_cvt_pk_bf16_f32 v184, v190, v191
	v_add_f32_e32 v151, v151, v229
	v_cvt_pk_bf16_f32 v185, v192, v193
	s_waitcnt lgkmcnt(0)
	v_mfma_f32_32x32x16_bf16 v[50:65], v[164:167], v[178:181], v[50:65]
	v_mfma_f32_32x32x16_bf16 v[34:49], v[168:171], v[178:181], v[34:49]
	v_mfma_f32_32x32x16_bf16 v[50:65], v[232:235], v[182:185], v[50:65]
	v_mfma_f32_32x32x16_bf16 v[34:49], v[236:239], v[182:185], v[34:49]
	v_cmp_lt_i32_e32 vcc, 0, v231
	s_nop 1
	v_cndmask_b32_e32 v98, v98, v218, vcc
	v_cmp_lt_i32_e32 vcc, 1, v231
	s_nop 1
	v_cndmask_b32_e32 v99, v99, v218, vcc
	v_cmp_lt_i32_e32 vcc, 2, v231
	s_nop 1
	v_cndmask_b32_e32 v100, v100, v218, vcc
	v_cmp_lt_i32_e32 vcc, 3, v231
	s_nop 1
	v_cndmask_b32_e32 v101, v101, v218, vcc
	v_cmp_lt_i32_e32 vcc, 4, v231
	s_nop 1
	v_cndmask_b32_e32 v102, v102, v218, vcc
	v_cmp_lt_i32_e32 vcc, 5, v231
	s_nop 1
	v_cndmask_b32_e32 v103, v103, v218, vcc
	v_cmp_lt_i32_e32 vcc, 6, v231
	s_nop 1
	v_cndmask_b32_e32 v104, v104, v218, vcc
	v_cmp_lt_i32_e32 vcc, 7, v231
	s_nop 1
	v_cndmask_b32_e32 v105, v105, v218, vcc
	v_cmp_lt_i32_e32 vcc, 16, v231
	s_nop 1
	v_cndmask_b32_e32 v106, v106, v218, vcc
	v_cmp_lt_i32_e32 vcc, 17, v231
	s_nop 1
	v_cndmask_b32_e32 v107, v107, v218, vcc
	v_cmp_lt_i32_e32 vcc, 18, v231
	s_nop 1
	v_cndmask_b32_e32 v108, v108, v218, vcc
	v_cmp_lt_i32_e32 vcc, 19, v231
	s_nop 1
	v_cndmask_b32_e32 v109, v109, v218, vcc
	v_cmp_lt_i32_e32 vcc, 20, v231
	s_nop 1
	v_cndmask_b32_e32 v110, v110, v218, vcc
	v_cmp_lt_i32_e32 vcc, 21, v231
	s_nop 1
	v_cndmask_b32_e32 v111, v111, v218, vcc
	v_cmp_lt_i32_e32 vcc, 22, v231
	s_nop 1
	v_cndmask_b32_e32 v112, v112, v218, vcc
	v_cmp_lt_i32_e32 vcc, 23, v231
	s_nop 1
	v_cndmask_b32_e32 v113, v113, v218, vcc
	v_max_f32_e32 v229, v98, v99
	v_max3_f32 v229, v229, v100, v101
	v_max3_f32 v229, v229, v102, v103
	v_max3_f32 v229, v229, v104, v105
	v_max3_f32 v229, v229, v106, v107
	v_max3_f32 v229, v229, v108, v109
	v_max3_f32 v229, v229, v110, v111
	v_max3_f32 v229, v229, v112, v113
	v_mov_b32_e32 v230, v229
	s_nop 1
	v_permlane32_swap_b32_e32 v229, v230
	v_max_f32_e32 v229, v229, v230
	v_cmp_lt_f32_e32 vcc, s3, v229
	s_cbranch_vccnz .Lb_resc_m_2
.Lb_resc_m_2_ret:
	v_exp_f32_e32 v98, v98
	v_exp_f32_e32 v99, v99
	v_exp_f32_e32 v100, v100
	v_exp_f32_e32 v101, v101
	v_add_f32_e32 v229, v99, v98
	v_exp_f32_e32 v102, v102
	v_add_f32_e32 v229, v100, v229
	v_exp_f32_e32 v103, v103
	v_add_f32_e32 v229, v101, v229
	v_exp_f32_e32 v104, v104
	v_add_f32_e32 v229, v102, v229
	v_exp_f32_e32 v105, v105
	v_add_f32_e32 v229, v103, v229
	v_cvt_pk_bf16_f32 v98, v98, v99
	v_exp_f32_e32 v106, v106
	v_add_f32_e32 v229, v104, v229
	v_cvt_pk_bf16_f32 v99, v100, v101
	v_exp_f32_e32 v107, v107
	v_add_f32_e32 v229, v105, v229
	v_cvt_pk_bf16_f32 v100, v102, v103
	v_exp_f32_e32 v108, v108
	v_add_f32_e32 v229, v106, v229
	v_cvt_pk_bf16_f32 v101, v104, v105
	v_exp_f32_e32 v109, v109
	v_add_f32_e32 v229, v107, v229
	v_exp_f32_e32 v110, v110
	v_add_f32_e32 v229, v108, v229
	v_exp_f32_e32 v111, v111
	v_add_f32_e32 v229, v109, v229
	v_exp_f32_e32 v112, v112
	v_add_f32_e32 v229, v110, v229
	v_exp_f32_e32 v113, v113
	v_add_f32_e32 v229, v111, v229
	v_cvt_pk_bf16_f32 v102, v106, v107
	v_add_f32_e32 v229, v112, v229
	v_cvt_pk_bf16_f32 v103, v108, v109
	v_add_f32_e32 v229, v113, v229
	v_cvt_pk_bf16_f32 v104, v110, v111
	v_add_f32_e32 v150, v150, v229
	v_cvt_pk_bf16_f32 v105, v112, v113
	v_mfma_f32_32x32x16_bf16 v[18:33], v[164:167], v[98:101], v[18:33]
	v_mfma_f32_32x32x16_bf16 v[2:17], v[168:171], v[98:101], v[2:17]
	v_mfma_f32_32x32x16_bf16 v[18:33], v[232:235], v[102:105], v[18:33]
	v_mfma_f32_32x32x16_bf16 v[2:17], v[236:239], v[102:105], v[2:17]
	s_branch .Lb_next
.Lb_ep2:
	v_add_u32_e32 v219, s24, v153
	v_add_u32_e32 v220, s24, v154
	v_add_u32_e32 v223, s24, v155
	v_add_u32_e32 v224, s24, v156
	ds_read_b128 v[194:197], v219
	ds_read_b128 v[198:201], v220
	ds_read_b128 v[202:205], v223
	ds_read_b128 v[206:209], v224
	s_waitcnt lgkmcnt(0)
	v_mfma_f32_32x32x16_bf16 v[98:113], v[194:197], v[114:117], v[82:97]
	v_mfma_f32_32x32x16_bf16 v[98:113], v[198:201], v[122:125], v[98:113]
	v_mfma_f32_32x32x16_bf16 v[98:113], v[202:205], v[118:121], v[98:113]
	v_mfma_f32_32x32x16_bf16 v[98:113], v[206:209], v[126:129], v[98:113]
	v_add_u32_e32 v248, s24, v158
	ds_read_b128 v[164:167], v248 offset:8192
	ds_read_b128 v[168:171], v248 offset:12288
	v_add_u32_e32 v248, s24, v159
	ds_read_b128 v[232:235], v248 offset:8192
	ds_read_b128 v[236:239], v248 offset:12288
	s_nop 5
	v_cmp_gt_i32_e32 vcc, 0, v231
	s_nop 1
	v_cndmask_b32_e32 v98, v98, v218, vcc
	v_cmp_gt_i32_e32 vcc, 1, v231
	s_nop 1
	v_cndmask_b32_e32 v99, v99, v218, vcc
	v_cmp_gt_i32_e32 vcc, 2, v231
	s_nop 1
	v_cndmask_b32_e32 v100, v100, v218, vcc
	v_cmp_gt_i32_e32 vcc, 3, v231
	s_nop 1
	v_cndmask_b32_e32 v101, v101, v218, vcc
	v_cmp_gt_i32_e32 vcc, 4, v231
	s_nop 1
	v_cndmask_b32_e32 v102, v102, v218, vcc
	v_cmp_gt_i32_e32 vcc, 5, v231
	s_nop 1
	v_cndmask_b32_e32 v103, v103, v218, vcc
	v_cmp_gt_i32_e32 vcc, 6, v231
	s_nop 1
	v_cndmask_b32_e32 v104, v104, v218, vcc
	v_cmp_gt_i32_e32 vcc, 7, v231
	s_nop 1
	v_cndmask_b32_e32 v105, v105, v218, vcc
	v_cmp_gt_i32_e32 vcc, 16, v231
	s_nop 1
	v_cndmask_b32_e32 v106, v106, v218, vcc
	v_cmp_gt_i32_e32 vcc, 17, v231
	s_nop 1
	v_cndmask_b32_e32 v107, v107, v218, vcc
	v_cmp_gt_i32_e32 vcc, 18, v231
	s_nop 1
	v_cndmask_b32_e32 v108, v108, v218, vcc
	v_cmp_gt_i32_e32 vcc, 19, v231
	s_nop 1
	v_cndmask_b32_e32 v109, v109, v218, vcc
	v_cmp_gt_i32_e32 vcc, 20, v231
	s_nop 1
	v_cndmask_b32_e32 v110, v110, v218, vcc
	v_cmp_gt_i32_e32 vcc, 21, v231
	s_nop 1
	v_cndmask_b32_e32 v111, v111, v218, vcc
	v_cmp_gt_i32_e32 vcc, 22, v231
	s_nop 1
	v_cndmask_b32_e32 v112, v112, v218, vcc
	v_cmp_gt_i32_e32 vcc, 23, v231
	s_nop 1
	v_cndmask_b32_e32 v113, v113, v218, vcc
	v_max_f32_e32 v229, v98, v99
	v_max3_f32 v229, v229, v100, v101
	v_max3_f32 v229, v229, v102, v103
	v_max3_f32 v229, v229, v104, v105
	v_max3_f32 v229, v229, v106, v107
	v_max3_f32 v229, v229, v108, v109
	v_max3_f32 v229, v229, v110, v111
	v_max3_f32 v229, v229, v112, v113
	v_mov_b32_e32 v230, v229
	s_nop 1
	v_permlane32_swap_b32_e32 v229, v230
	v_max_f32_e32 v229, v229, v230
	v_cmp_lt_f32_e32 vcc, s3, v229
	s_cbranch_vccnz .Lb_resc_p_0

.Lb_resc_p_1_ret:
	s_waitcnt lgkmcnt(0)
	v_mfma_f32_32x32x16_bf16 v[98:113], v[194:197], v[130:133], v[66:81]
	v_exp_f32_e32 v178, v178
	v_exp_f32_e32 v179, v179
	v_exp_f32_e32 v180, v180
	v_exp_f32_e32 v181, v181
	v_add_f32_e32 v229, v179, v178
	v_exp_f32_e32 v182, v182
	v_add_f32_e32 v229, v180, v229
	v_mfma_f32_32x32x16_bf16 v[98:113], v[198:201], v[138:141], v[98:113]
	v_exp_f32_e32 v183, v183
	v_add_f32_e32 v229, v181, v229
	v_exp_f32_e32 v184, v184
	v_add_f32_e32 v229, v182, v229
	v_exp_f32_e32 v185, v185
	v_add_f32_e32 v229, v183, v229
	v_cvt_pk_bf16_f32 v178, v178, v179
	v_mfma_f32_32x32x16_bf16 v[98:113], v[202:205], v[134:137], v[98:113]
	v_exp_f32_e32 v186, v186
	v_add_f32_e32 v229, v184, v229
	v_cvt_pk_bf16_f32 v179, v180, v181
	v_exp_f32_e32 v187, v187
	v_add_f32_e32 v229, v185, v229
	v_cvt_pk_bf16_f32 v180, v182, v183
	v_exp_f32_e32 v188, v188
	v_mfma_f32_32x32x16_bf16 v[98:113], v[206:209], v[142:145], v[98:113]
	v_add_f32_e32 v229, v186, v229
	v_cvt_pk_bf16_f32 v181, v184, v185
	v_exp_f32_e32 v189, v189
	v_add_f32_e32 v229, v187, v229
	v_exp_f32_e32 v190, v190
	v_add_f32_e32 v229, v188, v229
	v_exp_f32_e32 v191, v191
	v_add_f32_e32 v229, v189, v229
	v_exp_f32_e32 v192, v192
	v_add_f32_e32 v229, v190, v229
	v_exp_f32_e32 v193, v193
	v_add_f32_e32 v229, v191, v229
	v_cvt_pk_bf16_f32 v182, v186, v187
	v_add_f32_e32 v229, v192, v229
	v_cvt_pk_bf16_f32 v183, v188, v189
	v_add_f32_e32 v229, v193, v229
	v_cvt_pk_bf16_f32 v184, v190, v191
	v_add_f32_e32 v150, v150, v229
	v_cvt_pk_bf16_f32 v185, v192, v193
	v_mfma_f32_32x32x16_bf16 v[18:33], v[164:167], v[178:181], v[18:33]
	v_mfma_f32_32x32x16_bf16 v[2:17], v[168:171], v[178:181], v[2:17]
	v_mfma_f32_32x32x16_bf16 v[18:33], v[232:235], v[182:185], v[18:33]
	v_mfma_f32_32x32x16_bf16 v[2:17], v[236:239], v[182:185], v[2:17]
	v_add_u32_e32 v248, s24, v160
	ds_read_b128 v[164:167], v248 offset:8192
	ds_read_b128 v[168:171], v248 offset:12288
	v_add_u32_e32 v248, s24, v161
	ds_read_b128 v[232:235], v248 offset:8192
	ds_read_b128 v[236:239], v248 offset:12288
	v_cmp_gt_i32_e32 vcc, 0, v231
	s_nop 1
	v_cndmask_b32_e32 v98, v98, v218, vcc
	v_cmp_gt_i32_e32 vcc, 1, v231
	s_nop 1
	v_cndmask_b32_e32 v99, v99, v218, vcc
	v_cmp_gt_i32_e32 vcc, 2, v231
	s_nop 1
	v_cndmask_b32_e32 v100, v100, v218, vcc
	v_cmp_gt_i32_e32 vcc, 3, v231
	s_nop 1
	v_cndmask_b32_e32 v101, v101, v218, vcc
	v_cmp_gt_i32_e32 vcc, 4, v231
	s_nop 1
	v_cndmask_b32_e32 v102, v102, v218, vcc
	v_cmp_gt_i32_e32 vcc, 5, v231
	s_nop 1
	v_cndmask_b32_e32 v103, v103, v218, vcc
	v_cmp_gt_i32_e32 vcc, 6, v231
	s_nop 1
	v_cndmask_b32_e32 v104, v104, v218, vcc
	v_cmp_gt_i32_e32 vcc, 7, v231
	s_nop 1
	v_cndmask_b32_e32 v105, v105, v218, vcc
	v_cmp_gt_i32_e32 vcc, 16, v231
	s_nop 1
	v_cndmask_b32_e32 v106, v106, v218, vcc
	v_cmp_gt_i32_e32 vcc, 17, v231
	s_nop 1
	v_cndmask_b32_e32 v107, v107, v218, vcc
	v_cmp_gt_i32_e32 vcc, 18, v231
	s_nop 1
	v_cndmask_b32_e32 v108, v108, v218, vcc
	v_cmp_gt_i32_e32 vcc, 19, v231
	s_nop 1
	v_cndmask_b32_e32 v109, v109, v218, vcc
	v_cmp_gt_i32_e32 vcc, 20, v231
	s_nop 1
	v_cndmask_b32_e32 v110, v110, v218, vcc
	v_cmp_gt_i32_e32 vcc, 21, v231
	s_nop 1
	v_cndmask_b32_e32 v111, v111, v218, vcc
	v_cmp_gt_i32_e32 vcc, 22, v231
	s_nop 1
	v_cndmask_b32_e32 v112, v112, v218, vcc
	v_cmp_gt_i32_e32 vcc, 23, v231
	s_nop 1
	v_cndmask_b32_e32 v113, v113, v218, vcc
	v_max_f32_e32 v229, v98, v99
	v_max3_f32 v229, v229, v100, v101
	v_max3_f32 v229, v229, v102, v103
	v_max3_f32 v229, v229, v104, v105
	v_max3_f32 v229, v229, v106, v107
	v_max3_f32 v229, v229, v108, v109
	v_max3_f32 v229, v229, v110, v111
	v_max3_f32 v229, v229, v112, v113
	v_mov_b32_e32 v230, v229
	s_nop 1
	v_permlane32_swap_b32_e32 v229, v230
	v_max_f32_e32 v229, v229, v230
	v_cmp_lt_f32_e32 vcc, s3, v229
	s_cbranch_vccnz .Lb_resc_p_2
.Lb_resc_p_2_ret:
	v_exp_f32_e32 v98, v98
	v_exp_f32_e32 v99, v99
	v_exp_f32_e32 v100, v100
	v_exp_f32_e32 v101, v101
	v_add_f32_e32 v229, v99, v98
	v_exp_f32_e32 v102, v102
	v_add_f32_e32 v229, v100, v229
	v_exp_f32_e32 v103, v103
	v_add_f32_e32 v229, v101, v229
	v_exp_f32_e32 v104, v104
	v_add_f32_e32 v229, v102, v229
	v_exp_f32_e32 v105, v105
	v_add_f32_e32 v229, v103, v229
	v_cvt_pk_bf16_f32 v98, v98, v99
	v_exp_f32_e32 v106, v106
	v_add_f32_e32 v229, v104, v229
	v_cvt_pk_bf16_f32 v99, v100, v101
	v_exp_f32_e32 v107, v107
	v_add_f32_e32 v229, v105, v229
	v_cvt_pk_bf16_f32 v100, v102, v103
	v_exp_f32_e32 v108, v108
	v_add_f32_e32 v229, v106, v229
	v_cvt_pk_bf16_f32 v101, v104, v105
	v_exp_f32_e32 v109, v109
	v_add_f32_e32 v229, v107, v229
	v_exp_f32_e32 v110, v110
	v_add_f32_e32 v229, v108, v229
	v_exp_f32_e32 v111, v111
	v_add_f32_e32 v229, v109, v229
	v_exp_f32_e32 v112, v112
	v_add_f32_e32 v229, v110, v229
	v_exp_f32_e32 v113, v113
	v_add_f32_e32 v229, v111, v229
	v_cvt_pk_bf16_f32 v102, v106, v107
	v_add_f32_e32 v229, v112, v229
	v_cvt_pk_bf16_f32 v103, v108, v109
	v_add_f32_e32 v229, v113, v229
	v_cvt_pk_bf16_f32 v104, v110, v111
	v_add_f32_e32 v150, v150, v229
	v_cvt_pk_bf16_f32 v105, v112, v113
	s_waitcnt lgkmcnt(0)
	v_mfma_f32_32x32x16_bf16 v[18:33], v[164:167], v[98:101], v[18:33]
	v_mfma_f32_32x32x16_bf16 v[2:17], v[168:171], v[98:101], v[2:17]
	v_mfma_f32_32x32x16_bf16 v[18:33], v[232:235], v[102:105], v[18:33]
	v_mfma_f32_32x32x16_bf16 v[2:17], v[236:239], v[102:105], v[2:17]
	s_branch .Lb_next
.Lb_next:
	s_mov_b64 s[18:19], 0x53000
	v_lshl_add_u64 v[148:149], v[148:149], 0, s[18:19]
	s_add_i32 s18, s95, 1
	s_add_i32 s19, s95, -1
	s_add_i32 s94, s94, 64
	s_addk_i32 s25, 0x4000
	v_lshl_add_u64 v[146:147], v[146:147], 0, s[26:27]
	s_cmp_lt_u32 s19, s78
	s_cbranch_scc0 .Lb_exit
	s_mov_b32 s95, s18
	s_branch .Lb_top
.Lb_exit:
	s_nop 15
	s_branch .LBB0_174
.Lb_resc_f_0:
	s_nop 15
	v_max_f32_e32 v230, 0, v229
	v_exp_f32_e64 v229, -v230
	v_add_f32_e32 v163, v163, v230
	v_sub_f32_e32 v98, v98, v230
	v_sub_f32_e32 v99, v99, v230
	v_sub_f32_e32 v100, v100, v230
	v_sub_f32_e32 v101, v101, v230
	v_sub_f32_e32 v102, v102, v230
	v_sub_f32_e32 v103, v103, v230
	v_sub_f32_e32 v104, v104, v230
	v_sub_f32_e32 v105, v105, v230
	v_sub_f32_e32 v106, v106, v230
	v_sub_f32_e32 v107, v107, v230
	v_sub_f32_e32 v108, v108, v230
	v_sub_f32_e32 v109, v109, v230
	v_sub_f32_e32 v110, v110, v230
	v_sub_f32_e32 v111, v111, v230
	v_sub_f32_e32 v112, v112, v230
	v_sub_f32_e32 v113, v113, v230
	v_mul_f32_e32 v50, v229, v50
	v_mul_f32_e32 v51, v229, v51
	v_mul_f32_e32 v52, v229, v52
	v_mul_f32_e32 v53, v229, v53
	v_mul_f32_e32 v54, v229, v54
	v_mul_f32_e32 v55, v229, v55
	v_mul_f32_e32 v56, v229, v56
	v_mul_f32_e32 v57, v229, v57
	v_mul_f32_e32 v58, v229, v58
	v_mul_f32_e32 v59, v229, v59
	v_mul_f32_e32 v60, v229, v60
	v_mul_f32_e32 v61, v229, v61
	v_mul_f32_e32 v62, v229, v62
	v_mul_f32_e32 v63, v229, v63
	v_mul_f32_e32 v64, v229, v64
	v_mul_f32_e32 v65, v229, v65
	v_mul_f32_e32 v34, v229, v34
	v_mul_f32_e32 v35, v229, v35
	v_mul_f32_e32 v36, v229, v36
	v_mul_f32_e32 v37, v229, v37
	v_mul_f32_e32 v38, v229, v38
	v_mul_f32_e32 v39, v229, v39
	v_mul_f32_e32 v40, v229, v40
	v_mul_f32_e32 v41, v229, v41
	v_mul_f32_e32 v42, v229, v42
	v_mul_f32_e32 v43, v229, v43
	v_mul_f32_e32 v44, v229, v44
	v_mul_f32_e32 v45, v229, v45
	v_mul_f32_e32 v46, v229, v46
	v_mul_f32_e32 v47, v229, v47
	v_mul_f32_e32 v48, v229, v48
	v_mul_f32_e32 v49, v229, v49
	v_mul_f32_e32 v151, v229, v151
	v_xor_b32_e32 v82, 0x80000000, v163
	v_mov_b32_e32 v83, v82
	v_mov_b32_e32 v84, v82
	v_mov_b32_e32 v85, v82
	v_mov_b32_e32 v86, v82
	v_mov_b32_e32 v87, v82
	v_mov_b32_e32 v88, v82
	v_mov_b32_e32 v89, v82
	v_mov_b32_e32 v90, v82
	v_mov_b32_e32 v91, v82
	v_mov_b32_e32 v92, v82
	v_mov_b32_e32 v93, v82
	v_mov_b32_e32 v94, v82
	v_mov_b32_e32 v95, v82
	v_mov_b32_e32 v96, v82
	v_mov_b32_e32 v97, v82
	s_nop 1
	s_branch .Lb_resc_f_0_ret
.Lb_resc_f_1:
	s_nop 15
	v_max_f32_e32 v230, 0, v229
	v_exp_f32_e64 v229, -v230
	v_add_f32_e32 v157, v157, v230
	v_sub_f32_e32 v178, v178, v230
	v_sub_f32_e32 v179, v179, v230
	v_sub_f32_e32 v180, v180, v230
	v_sub_f32_e32 v181, v181, v230
	v_sub_f32_e32 v182, v182, v230
	v_sub_f32_e32 v183, v183, v230
	v_sub_f32_e32 v184, v184, v230
	v_sub_f32_e32 v185, v185, v230
	v_sub_f32_e32 v186, v186, v230
	v_sub_f32_e32 v187, v187, v230
	v_sub_f32_e32 v188, v188, v230
	v_sub_f32_e32 v189, v189, v230
	v_sub_f32_e32 v190, v190, v230
	v_sub_f32_e32 v191, v191, v230
	v_sub_f32_e32 v192, v192, v230
	v_sub_f32_e32 v193, v193, v230
	v_mul_f32_e32 v18, v229, v18
	v_mul_f32_e32 v19, v229, v19
	v_mul_f32_e32 v20, v229, v20
	v_mul_f32_e32 v21, v229, v21
	v_mul_f32_e32 v22, v229, v22
	v_mul_f32_e32 v23, v229, v23
	v_mul_f32_e32 v24, v229, v24
	v_mul_f32_e32 v25, v229, v25
	v_mul_f32_e32 v26, v229, v26
	v_mul_f32_e32 v27, v229, v27
	v_mul_f32_e32 v28, v229, v28
	v_mul_f32_e32 v29, v229, v29
	v_mul_f32_e32 v30, v229, v30
	v_mul_f32_e32 v31, v229, v31
	v_mul_f32_e32 v32, v229, v32
	v_mul_f32_e32 v33, v229, v33
	v_mul_f32_e32 v2, v229, v2
	v_mul_f32_e32 v3, v229, v3
	v_mul_f32_e32 v4, v229, v4
	v_mul_f32_e32 v5, v229, v5
	v_mul_f32_e32 v6, v229, v6
	v_mul_f32_e32 v7, v229, v7
	v_mul_f32_e32 v8, v229, v8
	v_mul_f32_e32 v9, v229, v9
	v_mul_f32_e32 v10, v229, v10
	v_mul_f32_e32 v11, v229, v11
	v_mul_f32_e32 v12, v229, v12
	v_mul_f32_e32 v13, v229, v13
	v_mul_f32_e32 v14, v229, v14
	v_mul_f32_e32 v15, v229, v15
	v_mul_f32_e32 v16, v229, v16
	v_mul_f32_e32 v17, v229, v17
	v_mul_f32_e32 v150, v229, v150
	v_xor_b32_e32 v66, 0x80000000, v157
	v_mov_b32_e32 v67, v66
	v_mov_b32_e32 v68, v66
	v_mov_b32_e32 v69, v66
	v_mov_b32_e32 v70, v66
	v_mov_b32_e32 v71, v66
	v_mov_b32_e32 v72, v66
	v_mov_b32_e32 v73, v66
	v_mov_b32_e32 v74, v66
	v_mov_b32_e32 v75, v66
	v_mov_b32_e32 v76, v66
	v_mov_b32_e32 v77, v66
	v_mov_b32_e32 v78, v66
	v_mov_b32_e32 v79, v66
	v_mov_b32_e32 v80, v66
	v_mov_b32_e32 v81, v66
	s_nop 1
	s_branch .Lb_resc_f_1_ret

.Lb_resc_m_1:
	s_nop 15
	v_max_f32_e32 v230, 0, v229
	v_exp_f32_e64 v229, -v230
	v_add_f32_e32 v163, v163, v230
	v_sub_f32_e32 v178, v178, v230
	v_sub_f32_e32 v179, v179, v230
	v_sub_f32_e32 v180, v180, v230
	v_sub_f32_e32 v181, v181, v230
	v_sub_f32_e32 v182, v182, v230
	v_sub_f32_e32 v183, v183, v230
	v_sub_f32_e32 v184, v184, v230
	v_sub_f32_e32 v185, v185, v230
	v_sub_f32_e32 v186, v186, v230
	v_sub_f32_e32 v187, v187, v230
	v_sub_f32_e32 v188, v188, v230
	v_sub_f32_e32 v189, v189, v230
	v_sub_f32_e32 v190, v190, v230
	v_sub_f32_e32 v191, v191, v230
	v_sub_f32_e32 v192, v192, v230
	v_sub_f32_e32 v193, v193, v230
	v_mul_f32_e32 v50, v229, v50
	v_mul_f32_e32 v51, v229, v51
	v_mul_f32_e32 v52, v229, v52
	v_mul_f32_e32 v53, v229, v53
	v_mul_f32_e32 v54, v229, v54
	v_mul_f32_e32 v55, v229, v55
	v_mul_f32_e32 v56, v229, v56
	v_mul_f32_e32 v57, v229, v57
	v_mul_f32_e32 v58, v229, v58
	v_mul_f32_e32 v59, v229, v59
	v_mul_f32_e32 v60, v229, v60
	v_mul_f32_e32 v61, v229, v61
	v_mul_f32_e32 v62, v229, v62
	v_mul_f32_e32 v63, v229, v63
	v_mul_f32_e32 v64, v229, v64
	v_mul_f32_e32 v65, v229, v65
	v_mul_f32_e32 v34, v229, v34
	v_mul_f32_e32 v35, v229, v35
	v_mul_f32_e32 v36, v229, v36
	v_mul_f32_e32 v37, v229, v37
	v_mul_f32_e32 v38, v229, v38
	v_mul_f32_e32 v39, v229, v39
	v_mul_f32_e32 v40, v229, v40
	v_mul_f32_e32 v41, v229, v41
	v_mul_f32_e32 v42, v229, v42
	v_mul_f32_e32 v43, v229, v43
	v_mul_f32_e32 v44, v229, v44
	v_mul_f32_e32 v45, v229, v45
	v_mul_f32_e32 v46, v229, v46
	v_mul_f32_e32 v47, v229, v47
	v_mul_f32_e32 v48, v229, v48
	v_mul_f32_e32 v49, v229, v49
	v_mul_f32_e32 v151, v229, v151
	v_xor_b32_e32 v82, 0x80000000, v163
	v_mov_b32_e32 v83, v82
	v_mov_b32_e32 v84, v82
	v_mov_b32_e32 v85, v82
	v_mov_b32_e32 v86, v82
	v_mov_b32_e32 v87, v82
	v_mov_b32_e32 v88, v82
	v_mov_b32_e32 v89, v82
	v_mov_b32_e32 v90, v82
	v_mov_b32_e32 v91, v82
	v_mov_b32_e32 v92, v82
	v_mov_b32_e32 v93, v82
	v_mov_b32_e32 v94, v82
	v_mov_b32_e32 v95, v82
	v_mov_b32_e32 v96, v82
	v_mov_b32_e32 v97, v82
	s_nop 1
	s_branch .Lb_resc_m_1_ret
.Lb_resc_m_2:
	s_nop 15
	v_max_f32_e32 v230, 0, v229
	v_exp_f32_e64 v229, -v230
	v_add_f32_e32 v157, v157, v230
	v_sub_f32_e32 v98, v98, v230
	v_sub_f32_e32 v99, v99, v230
	v_sub_f32_e32 v100, v100, v230
	v_sub_f32_e32 v101, v101, v230
	v_sub_f32_e32 v102, v102, v230
	v_sub_f32_e32 v103, v103, v230
	v_sub_f32_e32 v104, v104, v230
	v_sub_f32_e32 v105, v105, v230
	v_sub_f32_e32 v106, v106, v230
	v_sub_f32_e32 v107, v107, v230
	v_sub_f32_e32 v108, v108, v230
	v_sub_f32_e32 v109, v109, v230
	v_sub_f32_e32 v110, v110, v230
	v_sub_f32_e32 v111, v111, v230
	v_sub_f32_e32 v112, v112, v230
	v_sub_f32_e32 v113, v113, v230
	v_mul_f32_e32 v18, v229, v18
	v_mul_f32_e32 v19, v229, v19
	v_mul_f32_e32 v20, v229, v20
	v_mul_f32_e32 v21, v229, v21
	v_mul_f32_e32 v22, v229, v22
	v_mul_f32_e32 v23, v229, v23
	v_mul_f32_e32 v24, v229, v24
	v_mul_f32_e32 v25, v229, v25
	v_mul_f32_e32 v26, v229, v26
	v_mul_f32_e32 v27, v229, v27
	v_mul_f32_e32 v28, v229, v28
	v_mul_f32_e32 v29, v229, v29
	v_mul_f32_e32 v30, v229, v30
	v_mul_f32_e32 v31, v229, v31
	v_mul_f32_e32 v32, v229, v32
	v_mul_f32_e32 v33, v229, v33
	v_mul_f32_e32 v2, v229, v2
	v_mul_f32_e32 v3, v229, v3
	v_mul_f32_e32 v4, v229, v4
	v_mul_f32_e32 v5, v229, v5
	v_mul_f32_e32 v6, v229, v6
	v_mul_f32_e32 v7, v229, v7
	v_mul_f32_e32 v8, v229, v8
	v_mul_f32_e32 v9, v229, v9
	v_mul_f32_e32 v10, v229, v10
	v_mul_f32_e32 v11, v229, v11
	v_mul_f32_e32 v12, v229, v12
	v_mul_f32_e32 v13, v229, v13
	v_mul_f32_e32 v14, v229, v14
	v_mul_f32_e32 v15, v229, v15
	v_mul_f32_e32 v16, v229, v16
	v_mul_f32_e32 v17, v229, v17
	v_mul_f32_e32 v150, v229, v150
	v_xor_b32_e32 v66, 0x80000000, v157
	v_mov_b32_e32 v67, v66
	v_mov_b32_e32 v68, v66
	v_mov_b32_e32 v69, v66
	v_mov_b32_e32 v70, v66
	v_mov_b32_e32 v71, v66
	v_mov_b32_e32 v72, v66
	v_mov_b32_e32 v73, v66
	v_mov_b32_e32 v74, v66
	v_mov_b32_e32 v75, v66
	v_mov_b32_e32 v76, v66
	v_mov_b32_e32 v77, v66
	v_mov_b32_e32 v78, v66
	v_mov_b32_e32 v79, v66
	v_mov_b32_e32 v80, v66
	v_mov_b32_e32 v81, v66
	s_nop 1
	s_branch .Lb_resc_m_2_ret

.LBB0_378:
	s_sub_i32 s0, 0xa60, s28
	s_lshr_b32 s20, s0, 3
	s_cmp_eq_u32 s19, 3
	s_cselect_b64 vcc, -1, 0
	s_and_b64 s[0:1], vcc, exec
	s_cselect_b32 s8, 8, 0
	s_cselect_b32 s21, 12, 0
	s_cmp_lg_u32 s19, 1
	s_cselect_b64 s[42:43], -1, 0
	s_and_b64 s[0:1], s[42:43], exec
	s_cselect_b32 s18, s8, 16
	s_cmp_lg_u32 s19, 2
	s_cselect_b64 s[90:91], -1, 0
	s_cmp_eq_u32 s19, 2
	s_cselect_b64 s[0:1], -1, 0
	s_and_b64 s[8:9], s[0:1], exec
	s_cselect_b32 s8, 16, s21
	v_and_b32_e32 v0, 31, v178
	v_cmp_le_u32_e64 s[40:41], s8, v0
	v_cmp_gt_u32_e64 s[38:39], s18, v0
	s_and_b64 s[8:9], s[42:43], s[40:41]
	v_cmp_gt_u32_e64 s[36:37], s20, v0
	s_or_b64 s[8:9], s[38:39], s[8:9]
	s_and_b64 s[8:9], s[36:37], s[8:9]
	s_and_saveexec_b64 s[20:21], s[8:9]
	s_cbranch_execz .LBB0_380
	v_ashrrev_i32_e32 v6, 5, v179
	v_xor_b32_e32 v3, v6, v178
	v_lshlrev_b32_e32 v3, 4, v3
	v_lshlrev_b32_e32 v2, 9, v6
	v_and_b32_e32 v3, 0x1f0, v3
	v_add3_u32 v2, 0, v2, v3
	v_readlane_b32 s8, v253, 29
	ds_read_b128 v[2:5], v2
	v_readlane_b32 s9, v253, 30
	v_add_u32_e32 v8, s79, v6
	s_movk_i32 s5, 0x14c0
	v_mov_b64_e32 v[6:7], s[8:9]
	v_mad_i64_i32 v[8:9], s[8:9], v8, s5, v[6:7]
	s_lshl_b64 s[24:25], s[28:29], 1
	v_lshl_add_u64 v[8:9], v[8:9], 0, s[24:25]
	v_lshlrev_b32_e32 v0, 4, v0
	v_lshl_add_u64 v[8:9], v[8:9], 0, v[0:1]
	s_waitcnt lgkmcnt(0)
	global_store_dwordx4 v[8:9], v[2:5], off sc0 sc1
	s_movk_i32 s4, 0x14c0
	s_nop 0
	v_add_u32_e32 v2, 0x200, v179
	v_ashrrev_i32_e32 v8, 5, v2
	v_xor_b32_e32 v3, v8, v178
	v_lshlrev_b32_e32 v3, 4, v3
	v_lshlrev_b32_e32 v2, 9, v8
	v_and_b32_e32 v3, 0x1f0, v3
	v_add3_u32 v2, 0, v2, v3
	ds_read_b128 v[2:5], v2
	v_add_u32_e32 v8, s79, v8
	v_mad_i64_i32 v[8:9], s[8:9], v8, s5, v[6:7]
	v_lshl_add_u64 v[8:9], v[8:9], 0, s[24:25]
	v_lshl_add_u64 v[8:9], v[8:9], 0, v[0:1]
	s_waitcnt lgkmcnt(0)
	global_store_dwordx4 v[8:9], v[2:5], off sc0 sc1
	s_nop 1
	v_add_u32_e32 v2, 0x400, v179
	v_ashrrev_i32_e32 v8, 5, v2
	v_xor_b32_e32 v3, v8, v178
	v_lshlrev_b32_e32 v3, 4, v3
	v_lshlrev_b32_e32 v2, 9, v8
	v_and_b32_e32 v3, 0x1f0, v3
	v_add3_u32 v2, 0, v2, v3
	ds_read_b128 v[2:5], v2
	v_add_u32_e32 v8, s79, v8
	v_mad_i64_i32 v[8:9], s[8:9], v8, s5, v[6:7]
	v_lshl_add_u64 v[8:9], v[8:9], 0, s[24:25]
	v_lshl_add_u64 v[8:9], v[8:9], 0, v[0:1]
	s_waitcnt lgkmcnt(0)
	global_store_dwordx4 v[8:9], v[2:5], off sc0 sc1
	s_nop 1
	v_add_u32_e32 v2, 0x600, v179
	v_ashrrev_i32_e32 v8, 5, v2
	v_xor_b32_e32 v3, v8, v178
	v_lshlrev_b32_e32 v3, 4, v3
	v_lshlrev_b32_e32 v2, 9, v8
	v_and_b32_e32 v3, 0x1f0, v3
	v_add3_u32 v2, 0, v2, v3
	ds_read_b128 v[2:5], v2
	v_add_u32_e32 v8, s79, v8
	v_mad_i64_i32 v[8:9], s[8:9], v8, s5, v[6:7]
	v_lshl_add_u64 v[8:9], v[8:9], 0, s[24:25]
	v_lshl_add_u64 v[8:9], v[8:9], 0, v[0:1]
	s_waitcnt lgkmcnt(0)
	global_store_dwordx4 v[8:9], v[2:5], off sc0 sc1
	s_nop 1
	v_add_u32_e32 v2, 0x800, v179
	v_ashrrev_i32_e32 v8, 5, v2
	v_xor_b32_e32 v3, v8, v178
	v_lshlrev_b32_e32 v3, 4, v3
	v_lshlrev_b32_e32 v2, 9, v8
	v_and_b32_e32 v3, 0x1f0, v3
	v_add3_u32 v2, 0, v2, v3
	ds_read_b128 v[2:5], v2
	v_add_u32_e32 v8, s79, v8
	v_mad_i64_i32 v[8:9], s[8:9], v8, s5, v[6:7]
	v_lshl_add_u64 v[8:9], v[8:9], 0, s[24:25]
	v_lshl_add_u64 v[8:9], v[8:9], 0, v[0:1]
	s_waitcnt lgkmcnt(0)
	global_store_dwordx4 v[8:9], v[2:5], off sc0 sc1
	s_nop 1
	v_add_u32_e32 v2, 0xa00, v179
	v_ashrrev_i32_e32 v8, 5, v2
	v_xor_b32_e32 v3, v8, v178
	v_lshlrev_b32_e32 v3, 4, v3
	v_lshlrev_b32_e32 v2, 9, v8
	v_and_b32_e32 v3, 0x1f0, v3
	v_add3_u32 v2, 0, v2, v3
	ds_read_b128 v[2:5], v2
	v_add_u32_e32 v8, s79, v8
	v_mad_i64_i32 v[8:9], s[8:9], v8, s5, v[6:7]
	v_lshl_add_u64 v[8:9], v[8:9], 0, s[24:25]
	v_lshl_add_u64 v[8:9], v[8:9], 0, v[0:1]
	s_waitcnt lgkmcnt(0)
	global_store_dwordx4 v[8:9], v[2:5], off sc0 sc1
	s_nop 1
	v_add_u32_e32 v2, 0xc00, v179
	v_ashrrev_i32_e32 v8, 5, v2
	v_xor_b32_e32 v3, v8, v178
	v_lshlrev_b32_e32 v3, 4, v3
	v_lshlrev_b32_e32 v2, 9, v8
	v_and_b32_e32 v3, 0x1f0, v3
	v_add3_u32 v2, 0, v2, v3
	ds_read_b128 v[2:5], v2
	v_add_u32_e32 v8, s79, v8
	v_mad_i64_i32 v[8:9], s[8:9], v8, s5, v[6:7]
	v_lshl_add_u64 v[8:9], v[8:9], 0, s[24:25]
	v_lshl_add_u64 v[8:9], v[8:9], 0, v[0:1]
	s_waitcnt lgkmcnt(0)
	global_store_dwordx4 v[8:9], v[2:5], off sc0 sc1
	s_nop 1
	v_add_u32_e32 v2, 0xe00, v179
	v_ashrrev_i32_e32 v8, 5, v2
	v_xor_b32_e32 v3, v8, v178
	v_lshlrev_b32_e32 v3, 4, v3
	v_lshlrev_b32_e32 v2, 9, v8
	v_and_b32_e32 v3, 0x1f0, v3
	v_add3_u32 v2, 0, v2, v3
	ds_read_b128 v[2:5], v2
	v_add_u32_e32 v8, s79, v8
	v_mad_i64_i32 v[8:9], s[8:9], v8, s5, v[6:7]
	v_lshl_add_u64 v[8:9], v[8:9], 0, s[24:25]
	v_lshl_add_u64 v[8:9], v[8:9], 0, v[0:1]
	s_waitcnt lgkmcnt(0)
	global_store_dwordx4 v[8:9], v[2:5], off sc0 sc1
	s_nop 1
	v_add_u32_e32 v2, 0x1000, v179
	v_ashrrev_i32_e32 v8, 5, v2
	v_xor_b32_e32 v3, v8, v178
	v_lshlrev_b32_e32 v3, 4, v3
	v_lshlrev_b32_e32 v2, 9, v8
	v_and_b32_e32 v3, 0x1f0, v3
	v_add3_u32 v2, 0, v2, v3
	ds_read_b128 v[2:5], v2
	v_add_u32_e32 v8, s79, v8
	v_mad_i64_i32 v[8:9], s[8:9], v8, s5, v[6:7]
	v_lshl_add_u64 v[8:9], v[8:9], 0, s[24:25]
	v_lshl_add_u64 v[8:9], v[8:9], 0, v[0:1]
	s_waitcnt lgkmcnt(0)
	global_store_dwordx4 v[8:9], v[2:5], off sc0 sc1
	s_nop 1
	v_add_u32_e32 v2, 0x1200, v179
	v_ashrrev_i32_e32 v8, 5, v2
	v_xor_b32_e32 v3, v8, v178
	v_lshlrev_b32_e32 v3, 4, v3
	v_lshlrev_b32_e32 v2, 9, v8
	v_and_b32_e32 v3, 0x1f0, v3
	v_add3_u32 v2, 0, v2, v3
	ds_read_b128 v[2:5], v2
	v_add_u32_e32 v8, s79, v8
	v_mad_i64_i32 v[8:9], s[8:9], v8, s5, v[6:7]
	v_lshl_add_u64 v[8:9], v[8:9], 0, s[24:25]
	v_lshl_add_u64 v[8:9], v[8:9], 0, v[0:1]
	s_waitcnt lgkmcnt(0)
	global_store_dwordx4 v[8:9], v[2:5], off sc0 sc1
	s_nop 1
	v_add_u32_e32 v2, 0x1400, v179
	v_ashrrev_i32_e32 v8, 5, v2
	v_xor_b32_e32 v3, v8, v178
	v_lshlrev_b32_e32 v3, 4, v3
	v_lshlrev_b32_e32 v2, 9, v8
	v_and_b32_e32 v3, 0x1f0, v3
	v_add3_u32 v2, 0, v2, v3
	ds_read_b128 v[2:5], v2
	v_add_u32_e32 v8, s79, v8
	v_mad_i64_i32 v[8:9], s[8:9], v8, s5, v[6:7]
	v_lshl_add_u64 v[8:9], v[8:9], 0, s[24:25]
	v_lshl_add_u64 v[8:9], v[8:9], 0, v[0:1]
	s_waitcnt lgkmcnt(0)
	global_store_dwordx4 v[8:9], v[2:5], off sc0 sc1
	s_nop 1
	v_add_u32_e32 v2, 0x1600, v179
	v_ashrrev_i32_e32 v8, 5, v2
	v_xor_b32_e32 v3, v8, v178
	v_lshlrev_b32_e32 v3, 4, v3
	v_lshlrev_b32_e32 v2, 9, v8
	v_and_b32_e32 v3, 0x1f0, v3
	v_add3_u32 v2, 0, v2, v3
	ds_read_b128 v[2:5], v2
	v_add_u32_e32 v8, s79, v8
	v_mad_i64_i32 v[8:9], s[8:9], v8, s5, v[6:7]
	v_lshl_add_u64 v[8:9], v[8:9], 0, s[24:25]
	v_lshl_add_u64 v[8:9], v[8:9], 0, v[0:1]
	s_waitcnt lgkmcnt(0)
	global_store_dwordx4 v[8:9], v[2:5], off sc0 sc1
	s_nop 1
	v_add_u32_e32 v2, 0x1800, v179
	v_ashrrev_i32_e32 v8, 5, v2
	v_xor_b32_e32 v3, v8, v178
	v_lshlrev_b32_e32 v3, 4, v3
	v_lshlrev_b32_e32 v2, 9, v8
	v_and_b32_e32 v3, 0x1f0, v3
	v_add3_u32 v2, 0, v2, v3
	ds_read_b128 v[2:5], v2
	v_add_u32_e32 v8, s79, v8
	v_mad_i64_i32 v[8:9], s[8:9], v8, s5, v[6:7]
	v_lshl_add_u64 v[8:9], v[8:9], 0, s[24:25]
	v_lshl_add_u64 v[8:9], v[8:9], 0, v[0:1]
	s_waitcnt lgkmcnt(0)
	global_store_dwordx4 v[8:9], v[2:5], off sc0 sc1
	s_nop 1
	v_add_u32_e32 v2, 0x1a00, v179
	v_ashrrev_i32_e32 v8, 5, v2
	v_xor_b32_e32 v3, v8, v178
	v_lshlrev_b32_e32 v3, 4, v3
	v_lshlrev_b32_e32 v2, 9, v8
	v_and_b32_e32 v3, 0x1f0, v3
	v_add3_u32 v2, 0, v2, v3
	ds_read_b128 v[2:5], v2
	v_add_u32_e32 v8, s79, v8
	v_mad_i64_i32 v[8:9], s[8:9], v8, s5, v[6:7]
	v_lshl_add_u64 v[8:9], v[8:9], 0, s[24:25]
	v_lshl_add_u64 v[8:9], v[8:9], 0, v[0:1]
	s_waitcnt lgkmcnt(0)
	global_store_dwordx4 v[8:9], v[2:5], off sc0 sc1
	s_nop 1
	v_add_u32_e32 v2, 0x1c00, v179
	v_ashrrev_i32_e32 v8, 5, v2
	v_xor_b32_e32 v3, v8, v178
	v_lshlrev_b32_e32 v3, 4, v3
	v_lshlrev_b32_e32 v2, 9, v8
	v_and_b32_e32 v3, 0x1f0, v3
	v_add3_u32 v2, 0, v2, v3
	ds_read_b128 v[2:5], v2
	v_add_u32_e32 v8, s79, v8
	v_mad_i64_i32 v[8:9], s[8:9], v8, s5, v[6:7]
	v_lshl_add_u64 v[8:9], v[8:9], 0, s[24:25]
	v_lshl_add_u64 v[8:9], v[8:9], 0, v[0:1]
	s_waitcnt lgkmcnt(0)
	global_store_dwordx4 v[8:9], v[2:5], off sc0 sc1
	s_nop 1
	v_add_u32_e32 v2, 0x1e00, v179
	v_ashrrev_i32_e32 v8, 5, v2
	v_xor_b32_e32 v3, v8, v178
	v_lshlrev_b32_e32 v3, 4, v3
	v_lshlrev_b32_e32 v2, 9, v8
	v_and_b32_e32 v3, 0x1f0, v3
	v_add3_u32 v2, 0, v2, v3
	ds_read_b128 v[2:5], v2
	v_add_u32_e32 v8, s79, v8
	v_mad_i64_i32 v[6:7], s[8:9], v8, s5, v[6:7]
	v_lshl_add_u64 v[6:7], v[6:7], 0, s[24:25]
	v_lshl_add_u64 v[6:7], v[6:7], 0, v[0:1]
	s_waitcnt lgkmcnt(0)
	global_store_dwordx4 v[6:7], v[2:5], off sc0 sc1

.LBB0_427:
	v_mad_i64_i32 v[146:147], s[18:19], v201, s4, v[160:161]
	global_store_dwordx4 v[146:147], v[2:5], off sc0 sc1
	s_andn2_b64 vcc, exec, s[94:95]
	s_cbranch_vccnz .LBB0_416
.LBB0_428:
	v_mad_i64_i32 v[146:147], s[18:19], v202, s4, v[160:161]
	global_store_dwordx4 v[146:147], v[6:9], off sc0 sc1
	s_andn2_b64 vcc, exec, s[30:31]
	s_cbranch_vccnz .LBB0_417
.LBB0_429:
	v_mad_i64_i32 v[146:147], s[18:19], v203, s4, v[160:161]
	global_store_dwordx4 v[146:147], v[10:13], off sc0 sc1
	s_andn2_b64 vcc, exec, s[0:1]
	s_cbranch_vccnz .LBB0_382
.LBB0_430:
	v_mad_i64_i32 v[146:147], s[0:1], v204, s4, v[160:161]
	global_store_dwordx4 v[146:147], v[14:17], off sc0 sc1
	s_branch .LBB0_382

.LBB0_432:
	s_add_i32 s0, 0, 0x20010
	v_lshl_add_u32 v146, v181, 2, s0
	ds_read2st64_b32 v[2:3], v146 offset1:2
	v_and_b32_e32 v6, 12, v180
	v_or_b32_e32 v4, v186, v6
	v_lshrrev_b32_e32 v8, 3, v181
	v_lshlrev_b32_e32 v0, 1, v185
	s_waitcnt lgkmcnt(0)
	v_mul_f32_e32 v5, v142, v2
	v_lshlrev_b32_e32 v7, 9, v4
	v_bitop3_b32 v4, v8, v180, 12 bitop3:0x78
	v_and_b32_e32 v0, 14, v0
	v_cvt_pk_bf16_f32 v9, v5, s0
	v_lshl_add_u32 v5, v4, 4, 0
	v_add3_u32 v4, v5, v7, v0
	ds_write_b16 v4, v9
	v_bitop3_b32 v9, v8, v6, 1 bitop3:0x1e
	v_mul_f32_e32 v4, v143, v2
	v_lshl_add_u32 v10, v9, 4, 0
	v_cvt_pk_bf16_f32 v4, v4, s0
	v_add3_u32 v9, v10, v7, v0
	ds_write_b16 v9, v4 offset:512
	v_bitop3_b32 v9, v8, v6, 2 bitop3:0x1e
	v_mul_f32_e32 v4, v144, v2
	v_lshl_add_u32 v11, v9, 4, 0
	v_cvt_pk_bf16_f32 v4, v4, s0
	v_add3_u32 v9, v11, v7, v0
	ds_write_b16 v9, v4 offset:1024
	v_bitop3_b32 v9, v8, v6, 3 bitop3:0x1e
	v_mul_f32_e32 v4, v145, v2
	v_lshl_add_u32 v12, v9, 4, 0
	v_cvt_pk_bf16_f32 v4, v4, s0
	v_add3_u32 v9, v12, v7, v0
	ds_write_b16 v9, v4 offset:1536
	v_bitop3_b32 v9, v8, v6, 16 bitop3:0x1e
	v_mul_f32_e32 v4, v138, v2
	v_lshl_add_u32 v13, v9, 4, 0
	v_cvt_pk_bf16_f32 v4, v4, s0
	v_add3_u32 v9, v13, v7, v0
	ds_write_b16 v9, v4 offset:8192
	v_bitop3_b32 v9, v8, v6, 17 bitop3:0x1e
	v_mul_f32_e32 v4, v139, v2
	v_lshl_add_u32 v14, v9, 4, 0
	v_cvt_pk_bf16_f32 v4, v4, s0
	v_add3_u32 v9, v14, v7, v0
	ds_write_b16 v9, v4 offset:8704
	v_bitop3_b32 v9, v8, v6, 18 bitop3:0x1e
	v_mul_f32_e32 v4, v140, v2
	v_lshl_add_u32 v15, v9, 4, 0
	v_cvt_pk_bf16_f32 v4, v4, s0
	v_add3_u32 v9, v15, v7, v0
	v_bitop3_b32 v8, v8, v6, 19 bitop3:0x1e
	ds_write_b16 v9, v4 offset:9216
	v_mul_f32_e32 v4, v141, v2
	v_lshl_add_u32 v16, v8, 4, 0
	v_cvt_pk_bf16_f32 v4, v4, s0
	v_add3_u32 v8, v16, v7, v0
	ds_write_b16 v8, v4 offset:9728
	v_lshl_add_u32 v4, v184, 2, s0
	ds_read_b32 v4, v4
	v_lshrrev_b32_e32 v8, 3, v184
	v_bitop3_b32 v17, v8, v180, 12 bitop3:0x78
	v_lshl_add_u32 v17, v17, 4, 0
	v_readlane_b32 s8, v253, 46
	s_waitcnt lgkmcnt(0)
	v_mul_f32_e32 v9, v134, v4
	v_cvt_pk_bf16_f32 v9, v9, s0
	v_add3_u32 v134, v17, v7, v0
	ds_write_b16 v134, v9
	v_bitop3_b32 v134, v8, v6, 1 bitop3:0x1e
	v_mul_f32_e32 v9, v135, v4
	v_lshl_add_u32 v134, v134, 4, 0
	v_cvt_pk_bf16_f32 v9, v9, s0
	v_add3_u32 v135, v134, v7, v0
	ds_write_b16 v135, v9 offset:512
	v_bitop3_b32 v135, v8, v6, 2 bitop3:0x1e
	v_mul_f32_e32 v9, v136, v4
	v_lshl_add_u32 v135, v135, 4, 0
	v_cvt_pk_bf16_f32 v9, v9, s0
	v_add3_u32 v136, v135, v7, v0
	ds_write_b16 v136, v9 offset:1024
	v_bitop3_b32 v136, v8, v6, 3 bitop3:0x1e
	v_mul_f32_e32 v9, v137, v4
	v_lshl_add_u32 v136, v136, 4, 0
	v_cvt_pk_bf16_f32 v9, v9, s0
	v_add3_u32 v137, v136, v7, v0
	ds_write_b16 v137, v9 offset:1536
	v_mul_f32_e32 v9, v130, v4
	v_bitop3_b32 v130, v8, v6, 16 bitop3:0x1e
	v_lshl_add_u32 v130, v130, 4, 0
	v_cvt_pk_bf16_f32 v9, v9, s0
	v_add3_u32 v137, v130, v7, v0
	ds_write_b16 v137, v9 offset:8192
	v_mul_f32_e32 v9, v131, v4
	v_bitop3_b32 v131, v8, v6, 17 bitop3:0x1e
	v_lshl_add_u32 v131, v131, 4, 0
	v_cvt_pk_bf16_f32 v9, v9, s0
	v_add3_u32 v137, v131, v7, v0
	ds_write_b16 v137, v9 offset:8704
	v_mul_f32_e32 v9, v132, v4
	v_bitop3_b32 v132, v8, v6, 18 bitop3:0x1e
	v_lshl_add_u32 v132, v132, 4, 0
	v_cvt_pk_bf16_f32 v9, v9, s0
	v_add3_u32 v137, v132, v7, v0
	v_bitop3_b32 v8, v8, v6, 19 bitop3:0x1e
	ds_write_b16 v137, v9 offset:9216
	v_mul_f32_e32 v9, v133, v4
	v_lshl_add_u32 v133, v8, 4, 0
	v_cvt_pk_bf16_f32 v9, v9, s0
	v_add3_u32 v8, v133, v7, v0
	ds_write_b16 v8, v9 offset:9728
	v_lshl_add_u32 v8, v183, 2, s0
	ds_read_b32 v137, v8
	v_lshrrev_b32_e32 v8, 3, v183
	s_movk_i32 s9, 0x80
	s_and_b32 s1, s79, 0x700
	s_lshl_b32 s28, s1, 1
	s_waitcnt lgkmcnt(0)
	v_mul_f32_e32 v9, v126, v137
	v_bitop3_b32 v126, v8, v180, 12 bitop3:0x78
	v_lshl_add_u32 v126, v126, 4, 0
	v_cvt_pk_bf16_f32 v9, v9, s0
	v_add3_u32 v138, v126, v7, v0
	ds_write_b16 v138, v9
	v_mul_f32_e32 v9, v127, v137
	v_bitop3_b32 v127, v8, v6, 1 bitop3:0x1e
	v_lshl_add_u32 v127, v127, 4, 0
	v_cvt_pk_bf16_f32 v9, v9, s0
	v_add3_u32 v138, v127, v7, v0
	ds_write_b16 v138, v9 offset:512
	v_mul_f32_e32 v9, v128, v137
	v_bitop3_b32 v128, v8, v6, 2 bitop3:0x1e
	v_lshl_add_u32 v128, v128, 4, 0
	v_cvt_pk_bf16_f32 v9, v9, s0
	v_add3_u32 v138, v128, v7, v0
	ds_write_b16 v138, v9 offset:1024
	v_mul_f32_e32 v9, v129, v137
	v_bitop3_b32 v129, v8, v6, 3 bitop3:0x1e
	v_lshl_add_u32 v129, v129, 4, 0
	v_cvt_pk_bf16_f32 v9, v9, s0
	v_add3_u32 v138, v129, v7, v0
	ds_write_b16 v138, v9 offset:1536
	v_mul_f32_e32 v9, v122, v137
	v_bitop3_b32 v122, v8, v6, 16 bitop3:0x1e
	v_lshl_add_u32 v122, v122, 4, 0
	v_cvt_pk_bf16_f32 v9, v9, s0
	v_add3_u32 v138, v122, v7, v0
	ds_write_b16 v138, v9 offset:8192
	v_mul_f32_e32 v9, v123, v137
	v_bitop3_b32 v123, v8, v6, 17 bitop3:0x1e
	v_lshl_add_u32 v123, v123, 4, 0
	v_cvt_pk_bf16_f32 v9, v9, s0
	v_add3_u32 v138, v123, v7, v0
	ds_write_b16 v138, v9 offset:8704
	v_mul_f32_e32 v9, v124, v137
	v_bitop3_b32 v124, v8, v6, 18 bitop3:0x1e
	v_lshl_add_u32 v124, v124, 4, 0
	v_cvt_pk_bf16_f32 v9, v9, s0
	v_add3_u32 v138, v124, v7, v0
	v_bitop3_b32 v8, v8, v6, 19 bitop3:0x1e
	ds_write_b16 v138, v9 offset:9216
	v_mul_f32_e32 v9, v125, v137
	v_lshl_add_u32 v125, v8, 4, 0
	v_cvt_pk_bf16_f32 v9, v9, s0
	v_add3_u32 v8, v125, v7, v0
	ds_write_b16 v8, v9 offset:9728
	v_lshl_add_u32 v8, v182, 2, s0
	ds_read_b32 v138, v8
	v_lshrrev_b32_e32 v8, 3, v182
	s_waitcnt lgkmcnt(0)
	v_mul_f32_e32 v9, v118, v138
	v_bitop3_b32 v118, v8, v180, 12 bitop3:0x78
	v_lshl_add_u32 v118, v118, 4, 0
	v_cvt_pk_bf16_f32 v9, v9, s0
	v_add3_u32 v139, v118, v7, v0
	ds_write_b16 v139, v9
	v_mul_f32_e32 v9, v119, v138
	v_bitop3_b32 v119, v8, v6, 1 bitop3:0x1e
	v_lshl_add_u32 v119, v119, 4, 0
	v_cvt_pk_bf16_f32 v9, v9, s0
	v_add3_u32 v139, v119, v7, v0
	ds_write_b16 v139, v9 offset:512
	v_mul_f32_e32 v9, v120, v138
	v_bitop3_b32 v120, v8, v6, 2 bitop3:0x1e
	v_lshl_add_u32 v120, v120, 4, 0
	v_cvt_pk_bf16_f32 v9, v9, s0
	v_add3_u32 v139, v120, v7, v0
	ds_write_b16 v139, v9 offset:1024
	v_mul_f32_e32 v9, v121, v138
	v_bitop3_b32 v121, v8, v6, 3 bitop3:0x1e
	v_lshl_add_u32 v121, v121, 4, 0
	v_cvt_pk_bf16_f32 v9, v9, s0
	v_add3_u32 v139, v121, v7, v0
	ds_write_b16 v139, v9 offset:1536
	v_mul_f32_e32 v9, v114, v138
	v_bitop3_b32 v114, v8, v6, 16 bitop3:0x1e
	v_lshl_add_u32 v114, v114, 4, 0
	v_cvt_pk_bf16_f32 v9, v9, s0
	v_add3_u32 v139, v114, v7, v0
	ds_write_b16 v139, v9 offset:8192
	v_mul_f32_e32 v9, v115, v138
	v_bitop3_b32 v115, v8, v6, 17 bitop3:0x1e
	v_lshl_add_u32 v115, v115, 4, 0
	v_cvt_pk_bf16_f32 v9, v9, s0
	v_add3_u32 v139, v115, v7, v0
	ds_write_b16 v139, v9 offset:8704
	v_mul_f32_e32 v9, v116, v138
	v_bitop3_b32 v116, v8, v6, 18 bitop3:0x1e
	v_lshl_add_u32 v116, v116, 4, 0
	v_cvt_pk_bf16_f32 v9, v9, s0
	v_add3_u32 v139, v116, v7, v0
	v_bitop3_b32 v8, v8, v6, 19 bitop3:0x1e
	ds_write_b16 v139, v9 offset:9216
	v_mul_f32_e32 v9, v117, v138
	v_lshl_add_u32 v117, v8, 4, 0
	v_cvt_pk_bf16_f32 v9, v9, s0
	v_add3_u32 v8, v117, v7, v0
	ds_write_b16 v8, v9 offset:9728
	v_mul_f32_e32 v8, v110, v2
	v_cvt_pk_bf16_f32 v9, v8, s0
	v_or_b32_e32 v8, 0x10000, v7
	v_add3_u32 v5, v5, v8, v0
	ds_write_b16 v5, v9
	v_mul_f32_e32 v5, v111, v2
	v_or_b32_e32 v9, 0x10200, v7
	v_cvt_pk_bf16_f32 v5, v5, s0
	v_add3_u32 v10, v10, v9, v0
	ds_write_b16 v10, v5
	v_mul_f32_e32 v5, v112, v2
	v_or_b32_e32 v10, 0x10400, v7
	v_cvt_pk_bf16_f32 v5, v5, s0
	v_add3_u32 v11, v11, v10, v0
	ds_write_b16 v11, v5
	v_mul_f32_e32 v5, v113, v2
	v_or_b32_e32 v11, 0x10600, v7
	v_cvt_pk_bf16_f32 v5, v5, s0
	v_add3_u32 v12, v12, v11, v0
	ds_write_b16 v12, v5
	v_mul_f32_e32 v5, v106, v2
	v_or_b32_e32 v12, 0x12000, v7
	v_cvt_pk_bf16_f32 v5, v5, s0
	v_add3_u32 v13, v13, v12, v0
	ds_write_b16 v13, v5
	v_mul_f32_e32 v5, v107, v2
	v_or_b32_e32 v13, 0x12200, v7
	v_cvt_pk_bf16_f32 v5, v5, s0
	v_add3_u32 v14, v14, v13, v0
	ds_write_b16 v14, v5
	v_mul_f32_e32 v5, v108, v2
	v_or_b32_e32 v14, 0x12400, v7
	v_cvt_pk_bf16_f32 v5, v5, s0
	v_add3_u32 v15, v15, v14, v0
	v_mul_f32_e32 v2, v109, v2
	ds_write_b16 v15, v5
	v_cvt_pk_bf16_f32 v5, v2, s0
	v_or_b32_e32 v2, 0x12600, v7
	v_add3_u32 v15, v16, v2, v0
	ds_write_b16 v15, v5
	v_mul_f32_e32 v5, v102, v4
	v_cvt_pk_bf16_f32 v5, v5, s0
	v_add3_u32 v15, v17, v8, v0
	ds_write_b16 v15, v5
	v_mul_f32_e32 v5, v103, v4
	v_cvt_pk_bf16_f32 v5, v5, s0
	v_add3_u32 v15, v134, v9, v0
	ds_write_b16 v15, v5
	v_mul_f32_e32 v5, v104, v4
	v_cvt_pk_bf16_f32 v5, v5, s0
	v_add3_u32 v15, v135, v10, v0
	ds_write_b16 v15, v5
	v_mul_f32_e32 v5, v105, v4
	v_cvt_pk_bf16_f32 v5, v5, s0
	v_add3_u32 v15, v136, v11, v0
	ds_write_b16 v15, v5
	v_mul_f32_e32 v5, v98, v4
	v_cvt_pk_bf16_f32 v5, v5, s0
	v_add3_u32 v15, v130, v12, v0
	ds_write_b16 v15, v5
	v_mul_f32_e32 v5, v99, v4
	v_cvt_pk_bf16_f32 v5, v5, s0
	v_add3_u32 v15, v131, v13, v0
	ds_write_b16 v15, v5
	v_mul_f32_e32 v5, v100, v4
	v_cvt_pk_bf16_f32 v5, v5, s0
	v_add3_u32 v15, v132, v14, v0
	v_mul_f32_e32 v4, v101, v4
	ds_write_b16 v15, v5
	v_cvt_pk_bf16_f32 v4, v4, s0
	v_add3_u32 v5, v133, v2, v0
	ds_write_b16 v5, v4
	v_mul_f32_e32 v4, v94, v137
	v_cvt_pk_bf16_f32 v4, v4, s0
	v_add3_u32 v5, v126, v8, v0
	ds_write_b16 v5, v4
	v_mul_f32_e32 v4, v95, v137
	v_cvt_pk_bf16_f32 v4, v4, s0
	v_add3_u32 v5, v127, v9, v0
	ds_write_b16 v5, v4
	v_mul_f32_e32 v4, v96, v137
	v_cvt_pk_bf16_f32 v4, v4, s0
	v_add3_u32 v5, v128, v10, v0
	ds_write_b16 v5, v4
	v_mul_f32_e32 v4, v97, v137
	v_cvt_pk_bf16_f32 v4, v4, s0
	v_add3_u32 v5, v129, v11, v0
	ds_write_b16 v5, v4
	v_mul_f32_e32 v4, v90, v137
	v_cvt_pk_bf16_f32 v4, v4, s0
	v_add3_u32 v5, v122, v12, v0
	ds_write_b16 v5, v4
	v_mul_f32_e32 v4, v91, v137
	v_cvt_pk_bf16_f32 v4, v4, s0
	v_add3_u32 v5, v123, v13, v0
	ds_write_b16 v5, v4
	v_mul_f32_e32 v4, v92, v137
	v_cvt_pk_bf16_f32 v4, v4, s0
	v_add3_u32 v5, v124, v14, v0
	ds_write_b16 v5, v4
	v_mul_f32_e32 v4, v93, v137
	v_cvt_pk_bf16_f32 v4, v4, s0
	v_add3_u32 v5, v125, v2, v0
	ds_write_b16 v5, v4
	v_mul_f32_e32 v4, v86, v138
	v_cvt_pk_bf16_f32 v4, v4, s0
	v_add3_u32 v5, v118, v8, v0
	ds_write_b16 v5, v4
	v_mul_f32_e32 v4, v87, v138
	v_cvt_pk_bf16_f32 v4, v4, s0
	v_add3_u32 v5, v119, v9, v0
	ds_write_b16 v5, v4
	v_mul_f32_e32 v4, v88, v138
	v_cvt_pk_bf16_f32 v4, v4, s0
	v_add3_u32 v5, v120, v10, v0
	ds_write_b16 v5, v4
	v_mul_f32_e32 v4, v89, v138
	v_cvt_pk_bf16_f32 v4, v4, s0
	v_add3_u32 v5, v121, v11, v0
	ds_write_b16 v5, v4
	v_mul_f32_e32 v4, v82, v138
	v_cvt_pk_bf16_f32 v4, v4, s0
	v_add3_u32 v5, v114, v12, v0
	ds_write_b16 v5, v4
	v_mul_f32_e32 v4, v83, v138
	v_cvt_pk_bf16_f32 v4, v4, s0
	v_add3_u32 v5, v115, v13, v0
	ds_write_b16 v5, v4
	v_mul_f32_e32 v4, v84, v138
	v_cvt_pk_bf16_f32 v4, v4, s0
	v_add3_u32 v5, v116, v14, v0
	ds_write_b16 v5, v4
	v_mul_f32_e32 v4, v85, v138
	v_cvt_pk_bf16_f32 v4, v4, s0
	v_add3_u32 v5, v117, v2, v0
	ds_write_b16 v5, v4
	v_add_u32_e32 v4, 0x80, v181
	v_lshrrev_b32_e32 v4, 3, v4
	v_bitop3_b32 v15, v4, v180, 12 bitop3:0x78
	v_mul_f32_e32 v5, v78, v3
	v_lshl_add_u32 v15, v15, 4, 0
	v_cvt_pk_bf16_f32 v5, v5, s0
	v_add3_u32 v16, v15, v7, v0
	ds_write_b16 v16, v5
	v_bitop3_b32 v16, v4, v6, 1 bitop3:0x1e
	v_mul_f32_e32 v5, v79, v3
	v_lshl_add_u32 v16, v16, 4, 0
	v_cvt_pk_bf16_f32 v5, v5, s0
	v_add3_u32 v17, v16, v7, v0
	ds_write_b16 v17, v5 offset:512
	v_bitop3_b32 v17, v4, v6, 2 bitop3:0x1e
	v_mul_f32_e32 v5, v80, v3
	v_lshl_add_u32 v17, v17, 4, 0
	v_cvt_pk_bf16_f32 v5, v5, s0
	v_add3_u32 v78, v17, v7, v0
	ds_write_b16 v78, v5 offset:1024
	v_bitop3_b32 v78, v4, v6, 3 bitop3:0x1e
	v_mul_f32_e32 v5, v81, v3
	v_lshl_add_u32 v78, v78, 4, 0
	v_cvt_pk_bf16_f32 v5, v5, s0
	v_add3_u32 v79, v78, v7, v0
	ds_write_b16 v79, v5 offset:1536
	v_mul_f32_e32 v5, v74, v3
	v_bitop3_b32 v74, v4, v6, 16 bitop3:0x1e
	v_lshl_add_u32 v74, v74, 4, 0
	v_cvt_pk_bf16_f32 v5, v5, s0
	v_add3_u32 v79, v74, v7, v0
	ds_write_b16 v79, v5 offset:8192
	v_mul_f32_e32 v5, v75, v3
	v_bitop3_b32 v75, v4, v6, 17 bitop3:0x1e
	v_lshl_add_u32 v75, v75, 4, 0
	v_cvt_pk_bf16_f32 v5, v5, s0
	v_add3_u32 v79, v75, v7, v0
	ds_write_b16 v79, v5 offset:8704
	v_mul_f32_e32 v5, v76, v3
	v_bitop3_b32 v76, v4, v6, 18 bitop3:0x1e
	v_lshl_add_u32 v76, v76, 4, 0
	v_cvt_pk_bf16_f32 v5, v5, s0
	v_add3_u32 v79, v76, v7, v0
	v_bitop3_b32 v4, v4, v6, 19 bitop3:0x1e
	ds_write_b16 v79, v5 offset:9216
	v_mul_f32_e32 v5, v77, v3
	v_lshl_add_u32 v77, v4, 4, 0
	v_cvt_pk_bf16_f32 v5, v5, s0
	v_add3_u32 v4, v77, v7, v0
	ds_write_b16 v4, v5 offset:9728
	ds_read2_b32 v[4:5], v146 offset0:144 offset1:160
	v_add_u32_e32 v79, 0x90, v181
	v_lshrrev_b32_e32 v79, 3, v79
	v_add3_u32 v15, v15, v8, v0
	s_waitcnt lgkmcnt(0)
	v_mul_f32_e32 v70, v70, v4
	v_cvt_pk_bf16_f32 v80, v70, s0
	v_bitop3_b32 v70, v79, v180, 12 bitop3:0x78
	v_lshl_add_u32 v70, v70, 4, 0
	v_add3_u32 v81, v70, v7, v0
	v_mul_f32_e32 v71, v71, v4
	ds_write_b16 v81, v80
	v_cvt_pk_bf16_f32 v80, v71, s0
	v_bitop3_b32 v71, v79, v6, 1 bitop3:0x1e
	v_lshl_add_u32 v71, v71, 4, 0
	v_add3_u32 v81, v71, v7, v0
	v_mul_f32_e32 v72, v72, v4
	ds_write_b16 v81, v80 offset:512
	v_cvt_pk_bf16_f32 v80, v72, s0
	v_bitop3_b32 v72, v79, v6, 2 bitop3:0x1e
	v_lshl_add_u32 v72, v72, 4, 0
	v_add3_u32 v81, v72, v7, v0
	v_mul_f32_e32 v73, v73, v4
	ds_write_b16 v81, v80 offset:1024
	v_cvt_pk_bf16_f32 v80, v73, s0
	v_bitop3_b32 v73, v79, v6, 3 bitop3:0x1e
	v_lshl_add_u32 v73, v73, 4, 0
	v_add3_u32 v81, v73, v7, v0
	v_mul_f32_e32 v66, v66, v4
	ds_write_b16 v81, v80 offset:1536
	v_cvt_pk_bf16_f32 v80, v66, s0
	v_bitop3_b32 v66, v79, v6, 16 bitop3:0x1e
	v_lshl_add_u32 v66, v66, 4, 0
	v_add3_u32 v81, v66, v7, v0
	v_mul_f32_e32 v67, v67, v4
	ds_write_b16 v81, v80 offset:8192
	v_cvt_pk_bf16_f32 v80, v67, s0
	v_bitop3_b32 v67, v79, v6, 17 bitop3:0x1e
	v_lshl_add_u32 v67, v67, 4, 0
	v_add3_u32 v81, v67, v7, v0
	v_mul_f32_e32 v68, v68, v4
	ds_write_b16 v81, v80 offset:8704
	v_cvt_pk_bf16_f32 v80, v68, s0
	v_bitop3_b32 v68, v79, v6, 18 bitop3:0x1e
	v_lshl_add_u32 v68, v68, 4, 0
	v_add3_u32 v81, v68, v7, v0
	v_mul_f32_e32 v69, v69, v4
	ds_write_b16 v81, v80 offset:9216
	v_cvt_pk_bf16_f32 v80, v69, s0
	v_bitop3_b32 v69, v79, v6, 19 bitop3:0x1e
	v_lshl_add_u32 v69, v69, 4, 0
	v_add3_u32 v79, v69, v7, v0
	ds_write_b16 v79, v80 offset:9728
	v_add_u32_e32 v79, 0xa0, v181
	v_lshrrev_b32_e32 v79, 3, v79
	v_mul_f32_e32 v62, v62, v5
	v_cvt_pk_bf16_f32 v80, v62, s0
	v_bitop3_b32 v62, v79, v180, 12 bitop3:0x78
	v_lshl_add_u32 v62, v62, 4, 0
	v_add3_u32 v81, v62, v7, v0
	v_mul_f32_e32 v63, v63, v5
	ds_write_b16 v81, v80
	v_cvt_pk_bf16_f32 v80, v63, s0
	v_bitop3_b32 v63, v79, v6, 1 bitop3:0x1e
	v_lshl_add_u32 v63, v63, 4, 0
	v_add3_u32 v81, v63, v7, v0
	v_mul_f32_e32 v64, v64, v5
	ds_write_b16 v81, v80 offset:512
	v_cvt_pk_bf16_f32 v80, v64, s0
	v_bitop3_b32 v64, v79, v6, 2 bitop3:0x1e
	v_lshl_add_u32 v64, v64, 4, 0
	v_add3_u32 v81, v64, v7, v0
	v_mul_f32_e32 v65, v65, v5
	ds_write_b16 v81, v80 offset:1024
	v_cvt_pk_bf16_f32 v80, v65, s0
	v_bitop3_b32 v65, v79, v6, 3 bitop3:0x1e
	v_lshl_add_u32 v65, v65, 4, 0
	v_add3_u32 v81, v65, v7, v0
	v_mul_f32_e32 v58, v58, v5
	ds_write_b16 v81, v80 offset:1536
	v_cvt_pk_bf16_f32 v80, v58, s0
	v_bitop3_b32 v58, v79, v6, 16 bitop3:0x1e
	v_lshl_add_u32 v58, v58, 4, 0
	v_add3_u32 v81, v58, v7, v0
	v_mul_f32_e32 v59, v59, v5
	ds_write_b16 v81, v80 offset:8192
	v_cvt_pk_bf16_f32 v80, v59, s0
	v_bitop3_b32 v59, v79, v6, 17 bitop3:0x1e
	v_lshl_add_u32 v59, v59, 4, 0
	v_add3_u32 v81, v59, v7, v0
	v_mul_f32_e32 v60, v60, v5
	ds_write_b16 v81, v80 offset:8704
	v_cvt_pk_bf16_f32 v80, v60, s0
	v_bitop3_b32 v60, v79, v6, 18 bitop3:0x1e
	v_lshl_add_u32 v60, v60, 4, 0
	v_add3_u32 v81, v60, v7, v0
	v_mul_f32_e32 v61, v61, v5
	ds_write_b16 v81, v80 offset:9216
	v_cvt_pk_bf16_f32 v80, v61, s0
	v_bitop3_b32 v61, v79, v6, 19 bitop3:0x1e
	v_lshl_add_u32 v61, v61, 4, 0
	v_add3_u32 v79, v61, v7, v0
	ds_write_b16 v79, v80 offset:9728
	ds_read_b32 v80, v146 offset:704
	v_add_u32_e32 v79, 0xb0, v181
	v_lshrrev_b32_e32 v79, 3, v79
	v_bitop3_b32 v81, v79, v180, 12 bitop3:0x78
	v_lshl_add_u32 v81, v81, 4, 0
	s_waitcnt lgkmcnt(0)
	v_mul_f32_e32 v54, v54, v80
	v_cvt_pk_bf16_f32 v54, v54, s0
	v_add3_u32 v82, v81, v7, v0
	ds_write_b16 v82, v54
	v_mul_f32_e32 v54, v55, v80
	v_bitop3_b32 v55, v79, v6, 1 bitop3:0x1e
	v_lshl_add_u32 v55, v55, 4, 0
	v_cvt_pk_bf16_f32 v54, v54, s0
	v_add3_u32 v82, v55, v7, v0
	ds_write_b16 v82, v54 offset:512
	v_mul_f32_e32 v54, v56, v80
	v_bitop3_b32 v56, v79, v6, 2 bitop3:0x1e
	v_lshl_add_u32 v56, v56, 4, 0
	v_cvt_pk_bf16_f32 v54, v54, s0
	v_add3_u32 v82, v56, v7, v0
	ds_write_b16 v82, v54 offset:1024
	v_mul_f32_e32 v54, v57, v80
	v_bitop3_b32 v57, v79, v6, 3 bitop3:0x1e
	v_lshl_add_u32 v57, v57, 4, 0
	v_cvt_pk_bf16_f32 v54, v54, s0
	v_add3_u32 v82, v57, v7, v0
	ds_write_b16 v82, v54 offset:1536
	v_bitop3_b32 v54, v79, v6, 16 bitop3:0x1e
	v_mul_f32_e32 v50, v50, v80
	v_lshl_add_u32 v54, v54, 4, 0
	v_cvt_pk_bf16_f32 v50, v50, s0
	v_add3_u32 v82, v54, v7, v0
	ds_write_b16 v82, v50 offset:8192
	v_mul_f32_e32 v50, v51, v80
	v_bitop3_b32 v51, v79, v6, 17 bitop3:0x1e
	v_lshl_add_u32 v51, v51, 4, 0
	v_cvt_pk_bf16_f32 v50, v50, s0
	v_add3_u32 v82, v51, v7, v0
	ds_write_b16 v82, v50 offset:8704
	v_mul_f32_e32 v50, v52, v80
	v_bitop3_b32 v52, v79, v6, 18 bitop3:0x1e
	v_lshl_add_u32 v52, v52, 4, 0
	v_cvt_pk_bf16_f32 v50, v50, s0
	v_add3_u32 v82, v52, v7, v0
	v_bitop3_b32 v6, v79, v6, 19 bitop3:0x1e
	ds_write_b16 v82, v50 offset:9216
	v_mul_f32_e32 v50, v53, v80
	v_lshl_add_u32 v6, v6, 4, 0
	v_cvt_pk_bf16_f32 v50, v50, s0
	v_add3_u32 v7, v6, v7, v0
	ds_write_b16 v7, v50 offset:9728
	v_mul_f32_e32 v7, v46, v3
	v_cvt_pk_bf16_f32 v7, v7, s0
	ds_write_b16 v15, v7
	v_mul_f32_e32 v7, v47, v3
	v_cvt_pk_bf16_f32 v7, v7, s0
	v_add3_u32 v15, v16, v9, v0
	ds_write_b16 v15, v7
	v_mul_f32_e32 v7, v48, v3
	v_cvt_pk_bf16_f32 v7, v7, s0
	v_add3_u32 v15, v17, v10, v0
	ds_write_b16 v15, v7
	v_mul_f32_e32 v7, v49, v3
	v_cvt_pk_bf16_f32 v7, v7, s0
	v_add3_u32 v15, v78, v11, v0
	ds_write_b16 v15, v7
	v_mul_f32_e32 v7, v42, v3
	v_cvt_pk_bf16_f32 v7, v7, s0
	v_add3_u32 v15, v74, v12, v0
	ds_write_b16 v15, v7
	v_mul_f32_e32 v7, v43, v3
	v_cvt_pk_bf16_f32 v7, v7, s0
	v_add3_u32 v15, v75, v13, v0
	ds_write_b16 v15, v7
	v_mul_f32_e32 v7, v44, v3
	v_cvt_pk_bf16_f32 v7, v7, s0
	v_add3_u32 v15, v76, v14, v0
	v_mul_f32_e32 v3, v45, v3
	ds_write_b16 v15, v7
	v_cvt_pk_bf16_f32 v3, v3, s0
	v_add3_u32 v7, v77, v2, v0
	ds_write_b16 v7, v3
	v_mul_f32_e32 v3, v38, v4
	v_cvt_pk_bf16_f32 v3, v3, s0
	v_add3_u32 v7, v70, v8, v0
	ds_write_b16 v7, v3
	v_mul_f32_e32 v3, v39, v4
	v_cvt_pk_bf16_f32 v3, v3, s0
	v_add3_u32 v7, v71, v9, v0
	ds_write_b16 v7, v3
	v_mul_f32_e32 v3, v40, v4
	v_cvt_pk_bf16_f32 v3, v3, s0
	v_add3_u32 v7, v72, v10, v0
	ds_write_b16 v7, v3
	v_mul_f32_e32 v3, v41, v4
	v_cvt_pk_bf16_f32 v3, v3, s0
	v_add3_u32 v7, v73, v11, v0
	ds_write_b16 v7, v3
	v_mul_f32_e32 v3, v34, v4
	v_cvt_pk_bf16_f32 v3, v3, s0
	v_add3_u32 v7, v66, v12, v0
	ds_write_b16 v7, v3
	v_mul_f32_e32 v3, v35, v4
	v_cvt_pk_bf16_f32 v3, v3, s0
	v_add3_u32 v7, v67, v13, v0
	ds_write_b16 v7, v3
	v_mul_f32_e32 v3, v36, v4
	v_cvt_pk_bf16_f32 v3, v3, s0
	v_add3_u32 v7, v68, v14, v0
	ds_write_b16 v7, v3
	v_mul_f32_e32 v3, v37, v4
	v_cvt_pk_bf16_f32 v3, v3, s0
	v_add3_u32 v4, v69, v2, v0
	ds_write_b16 v4, v3
	v_mul_f32_e32 v3, v30, v5
	v_cvt_pk_bf16_f32 v3, v3, s0
	v_add3_u32 v4, v62, v8, v0
	ds_write_b16 v4, v3
	v_mul_f32_e32 v3, v31, v5
	v_cvt_pk_bf16_f32 v3, v3, s0
	v_add3_u32 v4, v63, v9, v0
	ds_write_b16 v4, v3
	v_mul_f32_e32 v3, v32, v5
	v_cvt_pk_bf16_f32 v3, v3, s0
	v_add3_u32 v4, v64, v10, v0
	ds_write_b16 v4, v3
	v_mul_f32_e32 v3, v33, v5
	v_cvt_pk_bf16_f32 v3, v3, s0
	v_add3_u32 v4, v65, v11, v0
	ds_write_b16 v4, v3
	v_mul_f32_e32 v3, v26, v5
	v_cvt_pk_bf16_f32 v3, v3, s0
	v_add3_u32 v4, v58, v12, v0
	ds_write_b16 v4, v3
	v_mul_f32_e32 v3, v27, v5
	v_cvt_pk_bf16_f32 v3, v3, s0
	v_add3_u32 v4, v59, v13, v0
	ds_write_b16 v4, v3
	v_mul_f32_e32 v3, v28, v5
	v_cvt_pk_bf16_f32 v3, v3, s0
	v_add3_u32 v4, v60, v14, v0
	ds_write_b16 v4, v3
	v_mul_f32_e32 v3, v29, v5
	v_cvt_pk_bf16_f32 v3, v3, s0
	v_add3_u32 v4, v61, v2, v0
	ds_write_b16 v4, v3
	v_mul_f32_e32 v3, v22, v80
	v_cvt_pk_bf16_f32 v3, v3, s0
	v_add3_u32 v4, v81, v8, v0
	ds_write_b16 v4, v3
	v_mul_f32_e32 v3, v23, v80
	v_cvt_pk_bf16_f32 v3, v3, s0
	v_add3_u32 v4, v55, v9, v0
	ds_write_b16 v4, v3
	v_mul_f32_e32 v3, v24, v80
	v_cvt_pk_bf16_f32 v3, v3, s0
	v_add3_u32 v4, v56, v10, v0
	ds_write_b16 v4, v3
	v_mul_f32_e32 v3, v25, v80
	v_cvt_pk_bf16_f32 v3, v3, s0
	v_add3_u32 v4, v57, v11, v0
	ds_write_b16 v4, v3
	v_mul_f32_e32 v3, v18, v80
	v_cvt_pk_bf16_f32 v3, v3, s0
	v_add3_u32 v4, v54, v12, v0
	ds_write_b16 v4, v3
	v_mul_f32_e32 v3, v19, v80
	v_cvt_pk_bf16_f32 v3, v3, s0
	v_add3_u32 v4, v51, v13, v0
	ds_write_b16 v4, v3
	v_mul_f32_e32 v3, v20, v80
	v_cvt_pk_bf16_f32 v3, v3, s0
	v_add3_u32 v4, v52, v14, v0
	ds_write_b16 v4, v3
	v_mul_f32_e32 v3, v21, v80
	v_cvt_pk_bf16_f32 v3, v3, s0
	v_add3_u32 v0, v6, v2, v0
	ds_write_b16 v0, v3
	v_ashrrev_i32_e32 v0, 5, v179
	v_xor_b32_e32 v3, v0, v178
	v_lshlrev_b32_e32 v3, 4, v3
	v_mov_b32_e32 v10, s8
	v_readlane_b32 s8, v253, 48
	s_lshl_b32 s0, s78, 4
	v_lshlrev_b32_e32 v2, 9, v0
	v_and_b32_e32 v3, 0x1f0, v3
	v_mov_b32_e32 v11, s8
	v_readlane_b32 s8, v253, 45
	s_and_b32 s0, s0, 0x1f80
	v_add3_u32 v2, 0, v2, v3
	v_cmp_gt_i32_e32 vcc, s9, v0
	v_mov_b32_e32 v12, s8
	v_readlane_b32 s8, v253, 47
	v_and_b32_e32 v0, 0x7f, v0
	s_waitcnt lgkmcnt(0)
	s_barrier
	ds_read_b128 v[2:5], v2
	v_mov_b32_e32 v13, s8
	v_or_b32_e32 v0, s0, v0
	v_cndmask_b32_e32 v7, v10, v11, vcc
	v_cndmask_b32_e32 v6, v12, v13, vcc
	v_mul_u32_u24_e32 v0, 0x1080, v0
	v_lshl_add_u64 v[6:7], v[6:7], 0, v[0:1]
	v_lshlrev_b32_e32 v0, 4, v178
	v_lshl_add_u64 v[6:7], v[6:7], 0, s[28:29]
	v_and_b32_e32 v0, 0x1f0, v0
	v_lshl_add_u64 v[6:7], v[6:7], 0, v[0:1]
	s_waitcnt lgkmcnt(0)
	global_store_dwordx4 v[6:7], v[2:5], off sc0 sc1
	v_mov_b32_e32 v9, v1
	s_nop 0
	v_add_u32_e32 v2, 0x200, v179
	v_ashrrev_i32_e32 v8, 5, v2
	v_xor_b32_e32 v3, v8, v178
	v_lshlrev_b32_e32 v3, 4, v3
	v_lshlrev_b32_e32 v2, 9, v8
	v_and_b32_e32 v3, 0x1f0, v3
	v_add3_u32 v2, 0, v2, v3
	v_cmp_gt_i32_e32 vcc, s9, v8
	v_and_b32_e32 v8, 0x7f, v8
	ds_read_b128 v[2:5], v2
	v_or_b32_e32 v8, s0, v8
	v_cndmask_b32_e32 v7, v10, v11, vcc
	v_cndmask_b32_e32 v6, v12, v13, vcc
	v_mul_u32_u24_e32 v8, 0x1080, v8
	v_lshl_add_u64 v[6:7], v[6:7], 0, v[8:9]
	v_lshl_add_u64 v[6:7], v[6:7], 0, s[28:29]
	v_lshl_add_u64 v[6:7], v[6:7], 0, v[0:1]
	s_waitcnt lgkmcnt(0)
	global_store_dwordx4 v[6:7], v[2:5], off sc0 sc1
	s_nop 1
	v_add_u32_e32 v2, 0x400, v179
	v_ashrrev_i32_e32 v8, 5, v2
	v_xor_b32_e32 v3, v8, v178
	v_lshlrev_b32_e32 v3, 4, v3
	v_lshlrev_b32_e32 v2, 9, v8
	v_and_b32_e32 v3, 0x1f0, v3
	v_add3_u32 v2, 0, v2, v3
	v_cmp_gt_i32_e32 vcc, s9, v8
	v_and_b32_e32 v8, 0x7f, v8
	ds_read_b128 v[2:5], v2
	v_or_b32_e32 v8, s0, v8
	v_cndmask_b32_e32 v7, v10, v11, vcc
	v_cndmask_b32_e32 v6, v12, v13, vcc
	v_mul_u32_u24_e32 v8, 0x1080, v8
	v_lshl_add_u64 v[6:7], v[6:7], 0, v[8:9]
	v_lshl_add_u64 v[6:7], v[6:7], 0, s[28:29]
	v_lshl_add_u64 v[6:7], v[6:7], 0, v[0:1]
	s_waitcnt lgkmcnt(0)
	global_store_dwordx4 v[6:7], v[2:5], off sc0 sc1
	s_nop 1
	v_add_u32_e32 v2, 0x600, v179
	v_ashrrev_i32_e32 v8, 5, v2
	v_xor_b32_e32 v3, v8, v178
	v_lshlrev_b32_e32 v3, 4, v3
	v_lshlrev_b32_e32 v2, 9, v8
	v_and_b32_e32 v3, 0x1f0, v3
	v_add3_u32 v2, 0, v2, v3
	v_cmp_gt_i32_e32 vcc, s9, v8
	v_and_b32_e32 v8, 0x7f, v8
	ds_read_b128 v[2:5], v2
	v_or_b32_e32 v8, s0, v8
	v_cndmask_b32_e32 v7, v10, v11, vcc
	v_cndmask_b32_e32 v6, v12, v13, vcc
	v_mul_u32_u24_e32 v8, 0x1080, v8
	v_lshl_add_u64 v[6:7], v[6:7], 0, v[8:9]
	v_lshl_add_u64 v[6:7], v[6:7], 0, s[28:29]
	v_lshl_add_u64 v[6:7], v[6:7], 0, v[0:1]
	s_waitcnt lgkmcnt(0)
	global_store_dwordx4 v[6:7], v[2:5], off sc0 sc1
	s_nop 1
	v_add_u32_e32 v2, 0x800, v179
	v_ashrrev_i32_e32 v8, 5, v2
	v_xor_b32_e32 v3, v8, v178
	v_lshlrev_b32_e32 v3, 4, v3
	v_lshlrev_b32_e32 v2, 9, v8
	v_and_b32_e32 v3, 0x1f0, v3
	v_add3_u32 v2, 0, v2, v3
	v_cmp_gt_i32_e32 vcc, s9, v8
	v_and_b32_e32 v8, 0x7f, v8
	ds_read_b128 v[2:5], v2
	v_or_b32_e32 v8, s0, v8
	v_cndmask_b32_e32 v7, v10, v11, vcc
	v_cndmask_b32_e32 v6, v12, v13, vcc
	v_mul_u32_u24_e32 v8, 0x1080, v8
	v_lshl_add_u64 v[6:7], v[6:7], 0, v[8:9]
	v_lshl_add_u64 v[6:7], v[6:7], 0, s[28:29]
	v_lshl_add_u64 v[6:7], v[6:7], 0, v[0:1]
	s_waitcnt lgkmcnt(0)
	global_store_dwordx4 v[6:7], v[2:5], off sc0 sc1
	s_nop 1
	v_add_u32_e32 v2, 0xa00, v179
	v_ashrrev_i32_e32 v8, 5, v2
	v_xor_b32_e32 v3, v8, v178
	v_lshlrev_b32_e32 v3, 4, v3
	v_lshlrev_b32_e32 v2, 9, v8
	v_and_b32_e32 v3, 0x1f0, v3
	v_add3_u32 v2, 0, v2, v3
	v_cmp_gt_i32_e32 vcc, s9, v8
	v_and_b32_e32 v8, 0x7f, v8
	ds_read_b128 v[2:5], v2
	v_or_b32_e32 v8, s0, v8
	v_cndmask_b32_e32 v7, v10, v11, vcc
	v_cndmask_b32_e32 v6, v12, v13, vcc
	v_mul_u32_u24_e32 v8, 0x1080, v8
	v_lshl_add_u64 v[6:7], v[6:7], 0, v[8:9]
	v_lshl_add_u64 v[6:7], v[6:7], 0, s[28:29]
	v_lshl_add_u64 v[6:7], v[6:7], 0, v[0:1]
	s_waitcnt lgkmcnt(0)
	global_store_dwordx4 v[6:7], v[2:5], off sc0 sc1
	s_nop 1
	v_add_u32_e32 v2, 0xc00, v179
	v_ashrrev_i32_e32 v8, 5, v2
	v_xor_b32_e32 v3, v8, v178
	v_lshlrev_b32_e32 v3, 4, v3
	v_lshlrev_b32_e32 v2, 9, v8
	v_and_b32_e32 v3, 0x1f0, v3
	v_add3_u32 v2, 0, v2, v3
	v_cmp_gt_i32_e32 vcc, s9, v8
	v_and_b32_e32 v8, 0x7f, v8
	ds_read_b128 v[2:5], v2
	v_or_b32_e32 v8, s0, v8
	v_cndmask_b32_e32 v7, v10, v11, vcc
	v_cndmask_b32_e32 v6, v12, v13, vcc
	v_mul_u32_u24_e32 v8, 0x1080, v8
	v_lshl_add_u64 v[6:7], v[6:7], 0, v[8:9]
	v_lshl_add_u64 v[6:7], v[6:7], 0, s[28:29]
	v_lshl_add_u64 v[6:7], v[6:7], 0, v[0:1]
	s_waitcnt lgkmcnt(0)
	global_store_dwordx4 v[6:7], v[2:5], off sc0 sc1
	s_nop 1
	v_add_u32_e32 v2, 0xe00, v179
	v_ashrrev_i32_e32 v8, 5, v2
	v_xor_b32_e32 v3, v8, v178
	v_lshlrev_b32_e32 v3, 4, v3
	v_lshlrev_b32_e32 v2, 9, v8
	v_and_b32_e32 v3, 0x1f0, v3
	v_add3_u32 v2, 0, v2, v3
	v_cmp_gt_i32_e32 vcc, s9, v8
	v_and_b32_e32 v8, 0x7f, v8
	ds_read_b128 v[2:5], v2
	v_or_b32_e32 v8, s0, v8
	v_cndmask_b32_e32 v7, v10, v11, vcc
	v_cndmask_b32_e32 v6, v12, v13, vcc
	v_mul_u32_u24_e32 v8, 0x1080, v8
	v_lshl_add_u64 v[6:7], v[6:7], 0, v[8:9]
	v_lshl_add_u64 v[6:7], v[6:7], 0, s[28:29]
	v_lshl_add_u64 v[6:7], v[6:7], 0, v[0:1]
	s_waitcnt lgkmcnt(0)
	global_store_dwordx4 v[6:7], v[2:5], off sc0 sc1
	s_nop 1
	v_add_u32_e32 v2, 0x1000, v179
	v_ashrrev_i32_e32 v8, 5, v2
	v_xor_b32_e32 v3, v8, v178
	v_lshlrev_b32_e32 v3, 4, v3
	v_lshlrev_b32_e32 v2, 9, v8
	v_and_b32_e32 v3, 0x1f0, v3
	v_add3_u32 v2, 0, v2, v3
	v_cmp_gt_i32_e32 vcc, s9, v8
	v_and_b32_e32 v8, 0x7f, v8
	ds_read_b128 v[2:5], v2
	v_or_b32_e32 v8, s0, v8
	v_cndmask_b32_e32 v7, v10, v11, vcc
	v_cndmask_b32_e32 v6, v12, v13, vcc
	v_mul_u32_u24_e32 v8, 0x1080, v8
	v_lshl_add_u64 v[6:7], v[6:7], 0, v[8:9]
	v_lshl_add_u64 v[6:7], v[6:7], 0, s[28:29]
	v_lshl_add_u64 v[6:7], v[6:7], 0, v[0:1]
	s_waitcnt lgkmcnt(0)
	global_store_dwordx4 v[6:7], v[2:5], off sc0 sc1
	s_nop 1
	v_add_u32_e32 v2, 0x1200, v179
	v_ashrrev_i32_e32 v8, 5, v2
	v_xor_b32_e32 v3, v8, v178
	v_lshlrev_b32_e32 v3, 4, v3
	v_lshlrev_b32_e32 v2, 9, v8
	v_and_b32_e32 v3, 0x1f0, v3
	v_add3_u32 v2, 0, v2, v3
	v_cmp_gt_i32_e32 vcc, s9, v8
	v_and_b32_e32 v8, 0x7f, v8
	ds_read_b128 v[2:5], v2
	v_or_b32_e32 v8, s0, v8
	v_cndmask_b32_e32 v7, v10, v11, vcc
	v_cndmask_b32_e32 v6, v12, v13, vcc
	v_mul_u32_u24_e32 v8, 0x1080, v8
	v_lshl_add_u64 v[6:7], v[6:7], 0, v[8:9]
	v_lshl_add_u64 v[6:7], v[6:7], 0, s[28:29]
	v_lshl_add_u64 v[6:7], v[6:7], 0, v[0:1]
	s_waitcnt lgkmcnt(0)
	global_store_dwordx4 v[6:7], v[2:5], off sc0 sc1
	s_nop 1
	v_add_u32_e32 v2, 0x1400, v179
	v_ashrrev_i32_e32 v8, 5, v2
	v_xor_b32_e32 v3, v8, v178
	v_lshlrev_b32_e32 v3, 4, v3
	v_lshlrev_b32_e32 v2, 9, v8
	v_and_b32_e32 v3, 0x1f0, v3
	v_add3_u32 v2, 0, v2, v3
	v_cmp_gt_i32_e32 vcc, s9, v8
	v_and_b32_e32 v8, 0x7f, v8
	ds_read_b128 v[2:5], v2
	v_or_b32_e32 v8, s0, v8
	v_cndmask_b32_e32 v7, v10, v11, vcc
	v_cndmask_b32_e32 v6, v12, v13, vcc
	v_mul_u32_u24_e32 v8, 0x1080, v8
	v_lshl_add_u64 v[6:7], v[6:7], 0, v[8:9]
	v_lshl_add_u64 v[6:7], v[6:7], 0, s[28:29]
	v_lshl_add_u64 v[6:7], v[6:7], 0, v[0:1]
	s_waitcnt lgkmcnt(0)
	global_store_dwordx4 v[6:7], v[2:5], off sc0 sc1
	s_nop 1
	v_add_u32_e32 v2, 0x1600, v179
	v_ashrrev_i32_e32 v8, 5, v2
	v_xor_b32_e32 v3, v8, v178
	v_lshlrev_b32_e32 v3, 4, v3
	v_lshlrev_b32_e32 v2, 9, v8
	v_and_b32_e32 v3, 0x1f0, v3
	v_add3_u32 v2, 0, v2, v3
	v_cmp_gt_i32_e32 vcc, s9, v8
	v_and_b32_e32 v8, 0x7f, v8
	ds_read_b128 v[2:5], v2
	v_or_b32_e32 v8, s0, v8
	v_cndmask_b32_e32 v7, v10, v11, vcc
	v_cndmask_b32_e32 v6, v12, v13, vcc
	v_mul_u32_u24_e32 v8, 0x1080, v8
	v_lshl_add_u64 v[6:7], v[6:7], 0, v[8:9]
	v_lshl_add_u64 v[6:7], v[6:7], 0, s[28:29]
	v_lshl_add_u64 v[6:7], v[6:7], 0, v[0:1]
	s_waitcnt lgkmcnt(0)
	global_store_dwordx4 v[6:7], v[2:5], off sc0 sc1
	s_nop 1
	v_add_u32_e32 v2, 0x1800, v179
	v_ashrrev_i32_e32 v8, 5, v2
	v_xor_b32_e32 v3, v8, v178
	v_lshlrev_b32_e32 v3, 4, v3
	v_lshlrev_b32_e32 v2, 9, v8
	v_and_b32_e32 v3, 0x1f0, v3
	v_add3_u32 v2, 0, v2, v3
	v_cmp_gt_i32_e32 vcc, s9, v8
	v_and_b32_e32 v8, 0x7f, v8
	ds_read_b128 v[2:5], v2
	v_or_b32_e32 v8, s0, v8
	v_cndmask_b32_e32 v7, v10, v11, vcc
	v_cndmask_b32_e32 v6, v12, v13, vcc
	v_mul_u32_u24_e32 v8, 0x1080, v8
	v_lshl_add_u64 v[6:7], v[6:7], 0, v[8:9]
	v_lshl_add_u64 v[6:7], v[6:7], 0, s[28:29]
	v_lshl_add_u64 v[6:7], v[6:7], 0, v[0:1]
	s_waitcnt lgkmcnt(0)
	global_store_dwordx4 v[6:7], v[2:5], off sc0 sc1
	s_nop 1
	v_add_u32_e32 v2, 0x1a00, v179
	v_ashrrev_i32_e32 v8, 5, v2
	v_xor_b32_e32 v3, v8, v178
	v_lshlrev_b32_e32 v3, 4, v3
	v_lshlrev_b32_e32 v2, 9, v8
	v_and_b32_e32 v3, 0x1f0, v3
	v_add3_u32 v2, 0, v2, v3
	v_cmp_gt_i32_e32 vcc, s9, v8
	v_and_b32_e32 v8, 0x7f, v8
	ds_read_b128 v[2:5], v2
	v_or_b32_e32 v8, s0, v8
	v_cndmask_b32_e32 v7, v10, v11, vcc
	v_cndmask_b32_e32 v6, v12, v13, vcc
	v_mul_u32_u24_e32 v8, 0x1080, v8
	v_lshl_add_u64 v[6:7], v[6:7], 0, v[8:9]
	v_lshl_add_u64 v[6:7], v[6:7], 0, s[28:29]
	v_lshl_add_u64 v[6:7], v[6:7], 0, v[0:1]
	s_waitcnt lgkmcnt(0)
	global_store_dwordx4 v[6:7], v[2:5], off sc0 sc1
	s_nop 1
	v_add_u32_e32 v2, 0x1c00, v179
	v_ashrrev_i32_e32 v8, 5, v2
	v_xor_b32_e32 v3, v8, v178
	v_lshlrev_b32_e32 v3, 4, v3
	v_lshlrev_b32_e32 v2, 9, v8
	v_and_b32_e32 v3, 0x1f0, v3
	v_add3_u32 v2, 0, v2, v3
	v_cmp_gt_i32_e32 vcc, s9, v8
	v_and_b32_e32 v8, 0x7f, v8
	ds_read_b128 v[2:5], v2
	v_or_b32_e32 v8, s0, v8
	v_cndmask_b32_e32 v7, v10, v11, vcc
	v_cndmask_b32_e32 v6, v12, v13, vcc
	v_mul_u32_u24_e32 v8, 0x1080, v8
	v_lshl_add_u64 v[6:7], v[6:7], 0, v[8:9]
	v_lshl_add_u64 v[6:7], v[6:7], 0, s[28:29]
	v_lshl_add_u64 v[6:7], v[6:7], 0, v[0:1]
	s_waitcnt lgkmcnt(0)
	global_store_dwordx4 v[6:7], v[2:5], off sc0 sc1
	s_nop 1
	v_add_u32_e32 v2, 0x1e00, v179
	v_ashrrev_i32_e32 v8, 5, v2
	v_xor_b32_e32 v3, v8, v178
	v_lshlrev_b32_e32 v3, 4, v3
	v_lshlrev_b32_e32 v2, 9, v8
	v_and_b32_e32 v3, 0x1f0, v3
	v_add3_u32 v2, 0, v2, v3
	v_cmp_gt_i32_e32 vcc, s9, v8
	v_and_b32_e32 v8, 0x7f, v8
	ds_read_b128 v[2:5], v2
	v_or_b32_e32 v8, s0, v8
	v_cndmask_b32_e32 v7, v10, v11, vcc
	v_cndmask_b32_e32 v6, v12, v13, vcc
	v_mul_u32_u24_e32 v8, 0x1080, v8
	v_lshl_add_u64 v[6:7], v[6:7], 0, v[8:9]
	v_lshl_add_u64 v[6:7], v[6:7], 0, s[28:29]
	v_lshl_add_u64 v[6:7], v[6:7], 0, v[0:1]
	s_waitcnt lgkmcnt(0)
	global_store_dwordx4 v[6:7], v[2:5], off sc0 sc1
	s_branch .LBB0_357
